# attn B: X/Y wave-half loop copies with staggered DMA singles, conflict-free K swizzle, counted LDS waits (A+B loops); out-proj epilogue loads batched
# speedup vs baseline: 1.0101x; 1.0101x over previous
; #define WBAR(n) do { asm volatile("s_waitcnt vmcnt(" #n ") lgkmcnt(0)" ::: "memory"); __builtin_amdgcn_s_barrier(); asm volatile("" ::: "memory"); } while (0)
; #define WBAR(n) do { asm volatile("s_waitcnt vmcnt(" #n ") lgkmcnt(0)" ::: "memory"); __builtin_amdgcn_s_barrier(); asm volatile("" ::: "memory"); } while (0)
; template <int LD> ...
;     ...
;   for (int j = 1; j + 1 < NT; j += 2) {
;     DMA_TILE(j + 1, 0, v2);
;     STEP(1, pB, ownA0, ownA1, ownB0, ownB1);
;     WBAR(0);
.LBB0_22:
	v_lshl_add_u64 v[166:167], vcc, 0, v[152:153]
	s_mov_b32 m0, s76
	s_mov_b32 s25, s24
	v_lshl_add_u64 v[168:169], vcc, 0, v[154:155]
	v_lshl_add_u64 v[80:81], v[166:167], 0, s[88:89]
	s_mov_b32 s24, s52
	s_mov_b32 s52, s26
	v_lshl_add_u64 v[158:159], vcc, 0, v[156:157]
	v_lshl_add_u64 v[82:83], v[168:169], 0, s[88:89]
	s_mov_b64 s[26:27], 0xea02000
	s_add_i32 s78, s62, s25
	global_load_lds_dwordx4 v[80:81], off
	s_mov_b32 m0, s77
	v_lshl_add_u64 v[84:85], v[158:159], 0, s[26:27]
	s_mov_b64 s[26:27], 0xea02080
	global_load_lds_dwordx4 v[82:83], off
	s_mov_b32 m0, s78
	v_lshl_add_u64 v[86:87], v[158:159], 0, s[26:27]
	s_mov_b64 s[26:27], 0xea02100
	global_load_lds_dwordx4 v[84:85], off
	s_add_i32 m0, s78, 0x400
	v_lshl_add_u64 v[88:89], v[158:159], 0, s[26:27]
	s_mov_b64 s[26:27], 0xea02180
	global_load_lds_dwordx4 v[86:87], off
	s_add_i32 m0, s78, 0x4000
	v_mov_b32_e32 v92, v172
	v_lshl_add_u64 v[90:91], v[158:159], 0, s[26:27]
	global_load_lds_dwordx4 v[88:89], off
	s_add_i32 m0, s78, 0x4400
	v_add_u32_e32 v177, s52, v217
	global_load_lds_dwordx4 v[90:91], off
	ds_read_b128 v[140:143], v171 offset:0
	ds_read_b128 v[136:139], v171 offset:0x400
	ds_read_b64_tr_b16 v[144:145], v177 offset:0
	ds_read_b64_tr_b16 v[146:147], v177 offset:0x800
	ds_read_b64_tr_b16 v[182:183], v177 offset:0x1000
	ds_read_b64_tr_b16 v[184:185], v177 offset:0x1800
	v_add_u32_e32 v160, s52, v151
	ds_read_b64_tr_b16 v[186:187], v160 offset:0
	ds_read_b64_tr_b16 v[188:189], v160 offset:0x800
	ds_read_b64_tr_b16 v[190:191], v160 offset:0x1000
	ds_read_b64_tr_b16 v[192:193], v160 offset:0x1800
	v_xad_u32 v181, v92, v178, v173
	ds_read_b128 v[194:197], v181 offset:0x4000
	v_xad_u32 v226, v92, v174, v173
	ds_read_b128 v[198:201], v226 offset:0x4000
	v_xad_u32 v227, v92, v175, v173
	ds_read_b128 v[218:221], v227 offset:0x4000
	v_xad_u32 v228, v92, v176, v173
	ds_read_b128 v[222:225], v228 offset:0x4000
	s_mov_b32 m0, s6
	s_waitcnt lgkmcnt(3)
	v_mfma_f32_32x32x16_bf16 v[80:95], v[194:197], v[120:123], v[64:79]
	s_mov_b64 s[26:27], 0xeb02000
	s_add_i32 s78, s62, s52
	v_mfma_f32_32x32x16_bf16 v[48:63], v[128:131], v[144:147], v[48:63]
	v_xor_b32_e32 v181, 0x80, v181
	ds_read_b128 v[144:147], v181 offset:0x4000
	v_add_u32_e32 v181, 0x24000, v179
	s_waitcnt lgkmcnt(3)
	v_mfma_f32_32x32x16_bf16 v[80:95], v[198:201], v[124:127], v[80:95]
	v_mfma_f32_32x32x16_bf16 v[48:63], v[132:135], v[182:185], v[48:63]
	v_xor_b32_e32 v226, 0x80, v226
	ds_read_b128 v[182:185], v226 offset:0x4000
	v_xor_b32_e32 v227, 0x80, v227
	ds_read_b128 v[194:197], v227 offset:0x4000
	v_xor_b32_e32 v228, 0x80, v228
	ds_read_b128 v[198:201], v228 offset:0x4000
	ds_read_b64_tr_b16 v[226:227], v177 offset:0x200
	ds_read_b64_tr_b16 v[228:229], v177 offset:0xa00
	s_waitcnt lgkmcnt(7)
	v_mfma_f32_32x32x16_bf16 v[80:95], v[218:221], v[112:115], v[80:95]
	ds_read_b64_tr_b16 v[218:219], v177 offset:0x1200
	ds_read_b64_tr_b16 v[220:221], v177 offset:0x1a00
	ds_read_b64_tr_b16 v[230:231], v160 offset:0x200
	ds_read_b64_tr_b16 v[232:233], v160 offset:0xa00
	ds_read_b64_tr_b16 v[234:235], v160 offset:0x1200
	ds_read_b64_tr_b16 v[236:237], v160 offset:0x1a00
	s_waitcnt lgkmcnt(12)
	v_mfma_f32_32x32x16_bf16 v[80:95], v[222:225], v[100:103], v[80:95]
	v_mfma_f32_32x32x16_bf16 v[48:63], v[140:143], v[186:189], v[48:63]
	ds_read_b64_tr_b16 v[186:187], v177 offset:0x400
	ds_read_b64_tr_b16 v[188:189], v177 offset:0xc00
	s_waitcnt lgkmcnt(8)
	v_mfma_f32_32x32x16_bf16 v[32:47], v[128:131], v[226:229], v[32:47]
	v_mfma_f32_32x32x16_bf16 v[80:95], v[144:147], v[96:99], v[80:95]
	v_mfma_f32_32x32x16_bf16 v[48:63], v[136:139], v[190:193], v[48:63]
	ds_read_b64_tr_b16 v[190:191], v177 offset:0x1400
	ds_read_b64_tr_b16 v[192:193], v177 offset:0x1c00
	s_waitcnt lgkmcnt(8)
	v_mfma_f32_32x32x16_bf16 v[32:47], v[132:135], v[218:221], v[32:47]
	ds_read_b64_tr_b16 v[218:219], v160 offset:0x400
	ds_read_b64_tr_b16 v[220:221], v160 offset:0xc00
	ds_read_b64_tr_b16 v[222:223], v160 offset:0x1400
	ds_read_b64_tr_b16 v[224:225], v160 offset:0x1c00
	s_nop 0
	v_mfma_f32_32x32x16_bf16 v[80:95], v[182:185], v[104:107], v[80:95]
	ds_read_b64_tr_b16 v[182:183], v177 offset:0x600
	ds_read_b64_tr_b16 v[184:185], v177 offset:0xe00
	s_waitcnt lgkmcnt(8)
	v_mfma_f32_32x32x16_bf16 v[16:31], v[128:131], v[186:189], v[16:31]
	ds_read_b64_tr_b16 v[186:187], v177 offset:0x1600
	ds_read_b64_tr_b16 v[188:189], v177 offset:0x1e00
	v_mfma_f32_32x32x16_bf16 v[80:95], v[194:197], v[108:111], v[80:95]
	s_waitcnt lgkmcnt(8)
	v_mfma_f32_32x32x16_bf16 v[16:31], v[132:135], v[190:193], v[16:31]
	ds_read_b64_tr_b16 v[190:191], v160 offset:0x600
	ds_read_b64_tr_b16 v[192:193], v160 offset:0xe00
	ds_read_b64_tr_b16 v[144:145], v160 offset:0x1600
	ds_read_b64_tr_b16 v[146:147], v160 offset:0x1e00
	s_nop 0
	s_nop 0
	s_waitcnt lgkmcnt(6)
	v_mfma_f32_32x32x16_bf16 v[0:15], v[128:131], v[182:185], v[0:15]
	v_lshl_add_u64 v[128:129], v[166:167], 0, s[90:91]
	v_lshl_add_u64 v[130:131], v[168:169], 0, s[90:91]
	v_lshl_add_u64 v[166:167], v[158:159], 0, s[26:27]
	s_mov_b64 s[26:27], 0xeb02080
	v_lshl_add_u64 v[168:169], v[158:159], 0, s[26:27]
	s_mov_b64 s[26:27], 0xeb02100
	v_lshl_add_u64 v[182:183], v[158:159], 0, s[26:27]
	v_mfma_f32_32x32x16_bf16 v[32:47], v[140:143], v[230:233], v[32:47]
	s_mov_b64 s[26:27], 0xeb02180
	v_mov_b32_e32 v184, v172
	v_lshl_add_u64 v[158:159], v[158:159], 0, s[26:27]
	s_mov_b32 s26, s25
	v_mfma_f32_32x32x16_bf16 v[80:95], v[198:201], v[116:119], v[80:95]
	s_waitcnt lgkmcnt(4)
	v_mfma_f32_32x32x16_bf16 v[0:15], v[132:135], v[186:189], v[0:15]
	s_nop 10
	v_exp_f32_e32 v238, v82
	v_exp_f32_e32 v239, v83
	v_exp_f32_e32 v240, v84
	v_exp_f32_e32 v241, v85
	v_exp_f32_e32 v242, v86
	v_exp_f32_e32 v243, v87
	v_exp_f32_e32 v244, v88
	v_mfma_f32_32x32x16_bf16 v[32:47], v[136:139], v[234:237], v[32:47]
	v_exp_f32_e32 v236, v80
	v_exp_f32_e32 v237, v81
	v_exp_f32_e32 v245, v89
	v_exp_f32_e32 v246, v90
	v_exp_f32_e32 v247, v91
	v_exp_f32_e32 v248, v92
	v_exp_f32_e32 v249, v93
	v_exp_f32_e32 v250, v94
	v_exp_f32_e32 v251, v95
	v_cvt_pk_bf16_f32 v132, v236, v237
	v_cvt_pk_bf16_f32 v133, v238, v239
	v_cvt_pk_bf16_f32 v134, v240, v241
	v_cvt_pk_bf16_f32 v135, v242, v243
	v_mfma_f32_32x32x16_bf16 v[16:31], v[140:143], v[218:221], v[16:31]
	v_add_u32_e32 v234, s24, v217
	v_add_u32_e32 v235, s24, v151
	s_waitcnt lgkmcnt(2)
	v_mfma_f32_32x32x16_bf16 v[0:15], v[140:143], v[190:193], v[0:15]
	v_cvt_pk_bf16_f32 v140, v244, v245
	v_cvt_pk_bf16_f32 v141, v246, v247
	v_cvt_pk_bf16_f32 v142, v248, v249
	v_cvt_pk_bf16_f32 v143, v250, v251
	ds_write_b128 v181, v[132:135]
	ds_write_b128 v181, v[140:143] offset:1024
	s_waitcnt vmcnt(0) lgkmcnt(0)
	s_barrier
; #define WBAR(n) do { asm volatile("s_waitcnt vmcnt(" #n ") lgkmcnt(0)" ::: "memory"); __builtin_amdgcn_s_barrier(); asm volatile("" ::: "memory"); } while (0)
; #define WBAR(n) do { asm volatile("s_waitcnt vmcnt(" #n ") lgkmcnt(0)" ::: "memory"); __builtin_amdgcn_s_barrier(); asm volatile("" ::: "memory"); } while (0)
; template <int LD> ...
;     ...
;     DMA_TILE(j + 2, 1, v2);
;     STEP(0, pA, ownB0, ownB1, ownA0, ownA1);
;     WBAR(0);
;     { const int t = v0; v0 = v1; v1 = v2; v2 = t; }
;   }
	global_load_lds_dwordx4 v[128:129], off
	s_mov_b32 m0, s7
	v_mfma_f32_32x32x16_bf16 v[16:31], v[136:139], v[222:225], v[16:31]
	global_load_lds_dwordx4 v[130:131], off
	s_mov_b32 m0, s78
	s_nop 0
	global_load_lds_dwordx4 v[166:167], off
	s_add_i32 m0, s78, 0x400
	v_mfma_f32_32x32x16_bf16 v[0:15], v[136:139], v[144:147], v[0:15]
	global_load_lds_dwordx4 v[168:169], off
	s_add_i32 m0, s78, 0x4000
	s_nop 0
	global_load_lds_dwordx4 v[182:183], off
	s_add_i32 m0, s78, 0x4400
	s_add_u32 vcc_lo, vcc_lo, 0x200000
	global_load_lds_dwordx4 v[158:159], off
	ds_read_b128 v[128:131], v171 offset:0x4000
	ds_read_b128 v[136:139], v171 offset:0x4400
	ds_read_b64_tr_b16 v[144:145], v234 offset:0
	ds_read_b64_tr_b16 v[146:147], v234 offset:0x800
	ds_read_b64_tr_b16 v[166:167], v234 offset:0x1000
	ds_read_b64_tr_b16 v[168:169], v234 offset:0x1800
	ds_read_b64_tr_b16 v[182:183], v235 offset:0
	s_nop 0
	v_xad_u32 v158, v184, v178, v173
	v_xad_u32 v159, v184, v174, v173
	v_xad_u32 v222, v184, v175, v173
	v_xad_u32 v223, v184, v176, v173
	ds_read_b64_tr_b16 v[184:185], v235 offset:0x800
	ds_read_b64_tr_b16 v[186:187], v235 offset:0x1000
	ds_read_b64_tr_b16 v[188:189], v235 offset:0x1800
	ds_read_b128 v[190:193], v158 offset:0
	ds_read_b128 v[194:197], v159 offset:0
	ds_read_b128 v[198:201], v222 offset:0
	ds_read_b128 v[218:221], v223 offset:0
	s_addc_u32 vcc_hi, vcc_hi, 0
	s_nop 0
	s_waitcnt lgkmcnt(3)
	v_mfma_f32_32x32x16_bf16 v[80:95], v[190:193], v[120:123], v[64:79]
	s_add_i32 s53, s53, 2
	s_cmp_ge_u32 s53, s51
	v_mfma_f32_32x32x16_bf16 v[48:63], v[132:135], v[144:147], v[48:63]
	v_xor_b32_e32 v158, 0x80, v158
	ds_read_b128 v[144:147], v158 offset:0
	s_waitcnt lgkmcnt(3)
	v_mfma_f32_32x32x16_bf16 v[80:95], v[194:197], v[124:127], v[80:95]
	v_mfma_f32_32x32x16_bf16 v[48:63], v[140:143], v[166:169], v[48:63]
	v_xor_b32_e32 v159, 0x80, v159
	ds_read_b128 v[166:169], v159 offset:0
	v_xor_b32_e32 v222, 0x80, v222
	ds_read_b128 v[190:193], v222 offset:0
	v_xor_b32_e32 v223, 0x80, v223
	ds_read_b128 v[194:197], v223 offset:0
	ds_read_b64_tr_b16 v[222:223], v234 offset:0x200
	ds_read_b64_tr_b16 v[224:225], v234 offset:0xa00
	s_waitcnt lgkmcnt(7)
	v_mfma_f32_32x32x16_bf16 v[80:95], v[198:201], v[112:115], v[80:95]
	ds_read_b64_tr_b16 v[198:199], v234 offset:0x1200
	ds_read_b64_tr_b16 v[200:201], v234 offset:0x1a00
	ds_read_b64_tr_b16 v[226:227], v235 offset:0x200
	ds_read_b64_tr_b16 v[228:229], v235 offset:0xa00
	ds_read_b64_tr_b16 v[230:231], v235 offset:0x1200
	ds_read_b64_tr_b16 v[232:233], v235 offset:0x1a00
	s_waitcnt lgkmcnt(12)
	v_mfma_f32_32x32x16_bf16 v[80:95], v[218:221], v[100:103], v[80:95]
	v_mfma_f32_32x32x16_bf16 v[48:63], v[128:131], v[182:185], v[48:63]
	ds_read_b64_tr_b16 v[182:183], v234 offset:0x400
	ds_read_b64_tr_b16 v[184:185], v234 offset:0xc00
	s_waitcnt lgkmcnt(8)
	v_mfma_f32_32x32x16_bf16 v[32:47], v[132:135], v[222:225], v[32:47]
	v_mfma_f32_32x32x16_bf16 v[80:95], v[144:147], v[96:99], v[80:95]
	v_mfma_f32_32x32x16_bf16 v[48:63], v[136:139], v[186:189], v[48:63]
	ds_read_b64_tr_b16 v[186:187], v234 offset:0x1400
	ds_read_b64_tr_b16 v[188:189], v234 offset:0x1c00
	s_waitcnt lgkmcnt(8)
	v_mfma_f32_32x32x16_bf16 v[32:47], v[140:143], v[198:201], v[32:47]
	ds_read_b64_tr_b16 v[198:199], v235 offset:0x400
	ds_read_b64_tr_b16 v[200:201], v235 offset:0xc00
	ds_read_b64_tr_b16 v[218:219], v235 offset:0x1400
	ds_read_b64_tr_b16 v[220:221], v235 offset:0x1c00
	s_nop 0
	ds_read_b64_tr_b16 v[144:145], v234 offset:0x600
	v_mfma_f32_32x32x16_bf16 v[80:95], v[166:169], v[104:107], v[80:95]
	ds_read_b64_tr_b16 v[146:147], v234 offset:0xe00
	ds_read_b64_tr_b16 v[166:167], v234 offset:0x1600
	s_waitcnt lgkmcnt(14)
	ds_read_b64_tr_b16 v[168:169], v234 offset:0x1e00
	s_waitcnt lgkmcnt(10)
	v_mfma_f32_32x32x16_bf16 v[16:31], v[132:135], v[182:185], v[16:31]
	ds_read_b64_tr_b16 v[182:183], v235 offset:0x600
	ds_read_b64_tr_b16 v[184:185], v235 offset:0xe00
	v_mfma_f32_32x32x16_bf16 v[80:95], v[190:193], v[108:111], v[80:95]
	s_waitcnt lgkmcnt(10)
	v_mfma_f32_32x32x16_bf16 v[16:31], v[140:143], v[186:189], v[16:31]
	ds_read_b64_tr_b16 v[186:187], v235 offset:0x1600
	ds_read_b64_tr_b16 v[188:189], v235 offset:0x1e00
	s_nop 0
	s_nop 0
	s_waitcnt lgkmcnt(6)
	v_mfma_f32_32x32x16_bf16 v[0:15], v[132:135], v[144:147], v[0:15]
	v_add_f32_e32 v132, v170, v236
	v_add_f32_e32 v132, v237, v132
	v_add_f32_e32 v132, v238, v132
	v_add_f32_e32 v132, v239, v132
	v_add_f32_e32 v132, v240, v132
	v_add_f32_e32 v132, v241, v132
	v_add_f32_e32 v132, v242, v132
	v_mfma_f32_32x32x16_bf16 v[80:95], v[194:197], v[116:119], v[80:95]
	v_add_f32_e32 v132, v243, v132
	v_add_f32_e32 v132, v244, v132
	v_add_f32_e32 v132, v245, v132
	v_add_f32_e32 v132, v246, v132
	v_add_f32_e32 v132, v247, v132
	v_add_f32_e32 v132, v248, v132
	v_add_f32_e32 v132, v249, v132
	s_waitcnt lgkmcnt(4)
	v_mfma_f32_32x32x16_bf16 v[0:15], v[140:143], v[166:169], v[0:15]
	s_nop 3
	v_exp_f32_e32 v80, v80
	v_exp_f32_e32 v81, v81
	v_add_f32_e32 v132, v250, v132
	v_exp_f32_e32 v82, v82
	v_add_f32_e32 v132, v251, v132
	v_exp_f32_e32 v83, v83
	v_exp_f32_e32 v84, v84
	v_mfma_f32_32x32x16_bf16 v[32:47], v[128:131], v[226:229], v[32:47]
	v_add_f32_e32 v140, v132, v80
	v_exp_f32_e32 v85, v85
	v_exp_f32_e32 v86, v86
	v_exp_f32_e32 v87, v87
	v_exp_f32_e32 v88, v88
	v_exp_f32_e32 v89, v89
	v_exp_f32_e32 v90, v90
	v_mfma_f32_32x32x16_bf16 v[16:31], v[128:131], v[198:201], v[16:31]
	v_exp_f32_e32 v91, v91
	v_exp_f32_e32 v92, v92
	v_exp_f32_e32 v93, v93
	v_exp_f32_e32 v94, v94
	v_exp_f32_e32 v95, v95
	v_cvt_pk_bf16_f32 v132, v88, v89
	v_cvt_pk_bf16_f32 v133, v90, v91
	s_waitcnt lgkmcnt(2)
	v_mfma_f32_32x32x16_bf16 v[0:15], v[128:131], v[182:185], v[0:15]
	v_cvt_pk_bf16_f32 v128, v80, v81
	v_add_f32_e32 v80, v81, v140
	v_add_f32_e32 v80, v82, v80
	v_add_f32_e32 v80, v83, v80
	v_add_f32_e32 v80, v84, v80
	v_add_f32_e32 v80, v85, v80
	v_add_f32_e32 v80, v86, v80
	v_add_f32_e32 v80, v87, v80
	v_mfma_f32_32x32x16_bf16 v[32:47], v[136:139], v[230:233], v[32:47]
	v_add_f32_e32 v80, v88, v80
	v_add_f32_e32 v80, v89, v80
	v_add_f32_e32 v80, v90, v80
	v_cvt_pk_bf16_f32 v129, v82, v83
	v_cvt_pk_bf16_f32 v130, v84, v85
	v_cvt_pk_bf16_f32 v131, v86, v87
	v_add_f32_e32 v80, v91, v80
	v_mfma_f32_32x32x16_bf16 v[16:31], v[136:139], v[218:221], v[16:31]
	v_cvt_pk_bf16_f32 v134, v92, v93
	v_cvt_pk_bf16_f32 v135, v94, v95
	ds_write_b128 v180, v[128:131]
	ds_write_b128 v180, v[132:135] offset:1024
	v_add_f32_e32 v80, v92, v80
	s_waitcnt vmcnt(0) lgkmcnt(0)
	s_barrier
	v_mfma_f32_32x32x16_bf16 v[0:15], v[136:139], v[186:189], v[0:15]
	v_add_f32_e32 v80, v93, v80
	v_add_f32_e32 v80, v94, v80
	v_add_f32_e32 v170, v95, v80
	s_cbranch_scc0 .LBB0_22
	s_branch .Lb_loop_done
; #define WBAR(n) do { asm volatile("s_waitcnt vmcnt(" #n ") lgkmcnt(0)" ::: "memory"); __builtin_amdgcn_s_barrier(); asm volatile("" ::: "memory"); } while (0)
; #define WBAR(n) do { asm volatile("s_waitcnt vmcnt(" #n ") lgkmcnt(0)" ::: "memory"); __builtin_amdgcn_s_barrier(); asm volatile("" ::: "memory"); } while (0)
; template <int LD> ...
;     ...
;   for (int j = 1; j + 1 < NT; j += 2) {
;     DMA_TILE(j + 1, 0, v2);
;     STEP(1, pB, ownA0, ownA1, ownB0, ownB1);
;     WBAR(0);
.Lb_loopY:
	v_lshl_add_u64 v[166:167], vcc, 0, v[152:153]
	s_mov_b32 s25, s24
	v_lshl_add_u64 v[168:169], vcc, 0, v[154:155]
	s_mov_b32 s24, s52
	s_mov_b32 s52, s26
	v_lshl_add_u64 v[158:159], vcc, 0, v[156:157]
	v_mov_b32_e32 v92, v172
	v_add_u32_e32 v177, s52, v217
	ds_read_b128 v[140:143], v171 offset:0
	ds_read_b128 v[136:139], v171 offset:0x400
	ds_read_b64_tr_b16 v[144:145], v177 offset:0
	ds_read_b64_tr_b16 v[146:147], v177 offset:0x800
	ds_read_b64_tr_b16 v[182:183], v177 offset:0x1000
	ds_read_b64_tr_b16 v[184:185], v177 offset:0x1800
	v_add_u32_e32 v160, s52, v151
	ds_read_b64_tr_b16 v[186:187], v160 offset:0
	ds_read_b64_tr_b16 v[188:189], v160 offset:0x800
	ds_read_b64_tr_b16 v[190:191], v160 offset:0x1000
	ds_read_b64_tr_b16 v[192:193], v160 offset:0x1800
	v_xad_u32 v181, v92, v178, v173
	ds_read_b128 v[194:197], v181 offset:0x4000
	v_xad_u32 v226, v92, v174, v173
	ds_read_b128 v[198:201], v226 offset:0x4000
	v_xad_u32 v227, v92, v175, v173
	ds_read_b128 v[218:221], v227 offset:0x4000
	v_xad_u32 v228, v92, v176, v173
	ds_read_b128 v[222:225], v228 offset:0x4000
	s_waitcnt lgkmcnt(3)
	v_mfma_f32_32x32x16_bf16 v[80:95], v[194:197], v[120:123], v[64:79]
	s_add_i32 s78, s62, s52
	v_mfma_f32_32x32x16_bf16 v[48:63], v[128:131], v[144:147], v[48:63]
	v_xor_b32_e32 v181, 0x80, v181
	ds_read_b128 v[144:147], v181 offset:0x4000
	v_add_u32_e32 v181, 0x24000, v179
	s_waitcnt lgkmcnt(3)
	v_mfma_f32_32x32x16_bf16 v[80:95], v[198:201], v[124:127], v[80:95]
	v_mfma_f32_32x32x16_bf16 v[48:63], v[132:135], v[182:185], v[48:63]
	v_xor_b32_e32 v226, 0x80, v226
	ds_read_b128 v[182:185], v226 offset:0x4000
	v_xor_b32_e32 v227, 0x80, v227
	ds_read_b128 v[194:197], v227 offset:0x4000
	v_xor_b32_e32 v228, 0x80, v228
	ds_read_b128 v[198:201], v228 offset:0x4000
	ds_read_b64_tr_b16 v[226:227], v177 offset:0x200
	ds_read_b64_tr_b16 v[228:229], v177 offset:0xa00
	s_waitcnt lgkmcnt(7)
	v_mfma_f32_32x32x16_bf16 v[80:95], v[218:221], v[112:115], v[80:95]
	ds_read_b64_tr_b16 v[218:219], v177 offset:0x1200
	ds_read_b64_tr_b16 v[220:221], v177 offset:0x1a00
	ds_read_b64_tr_b16 v[230:231], v160 offset:0x200
	ds_read_b64_tr_b16 v[232:233], v160 offset:0xa00
	ds_read_b64_tr_b16 v[234:235], v160 offset:0x1200
	ds_read_b64_tr_b16 v[236:237], v160 offset:0x1a00
	s_waitcnt lgkmcnt(12)
	v_mfma_f32_32x32x16_bf16 v[80:95], v[222:225], v[100:103], v[80:95]
	v_mfma_f32_32x32x16_bf16 v[48:63], v[140:143], v[186:189], v[48:63]
	s_mov_b32 m0, s76
	v_lshl_add_u64 v[254:255], v[166:167], 0, s[88:89]
	global_load_lds_dwordx4 v[254:255], off
	ds_read_b64_tr_b16 v[186:187], v177 offset:0x400
	ds_read_b64_tr_b16 v[188:189], v177 offset:0xc00
	s_waitcnt lgkmcnt(8)
	v_mfma_f32_32x32x16_bf16 v[32:47], v[128:131], v[226:229], v[32:47]
	v_mfma_f32_32x32x16_bf16 v[80:95], v[144:147], v[96:99], v[80:95]
	s_mov_b32 m0, s77
	v_lshl_add_u64 v[254:255], v[168:169], 0, s[88:89]
	global_load_lds_dwordx4 v[254:255], off
	v_mfma_f32_32x32x16_bf16 v[48:63], v[136:139], v[190:193], v[48:63]
	ds_read_b64_tr_b16 v[190:191], v177 offset:0x1400
	ds_read_b64_tr_b16 v[192:193], v177 offset:0x1c00
	s_waitcnt lgkmcnt(8)
	v_mfma_f32_32x32x16_bf16 v[32:47], v[132:135], v[218:221], v[32:47]
	s_add_i32 m0, s62, s25
	s_mov_b64 s[26:27], 0xea02000
	v_lshl_add_u64 v[254:255], v[158:159], 0, s[26:27]
	global_load_lds_dwordx4 v[254:255], off
	ds_read_b64_tr_b16 v[218:219], v160 offset:0x400
	ds_read_b64_tr_b16 v[220:221], v160 offset:0xc00
	ds_read_b64_tr_b16 v[222:223], v160 offset:0x1400
	ds_read_b64_tr_b16 v[224:225], v160 offset:0x1c00
	s_nop 0
	v_mfma_f32_32x32x16_bf16 v[80:95], v[182:185], v[104:107], v[80:95]
	ds_read_b64_tr_b16 v[182:183], v177 offset:0x600
	ds_read_b64_tr_b16 v[184:185], v177 offset:0xe00
	s_waitcnt lgkmcnt(8)
	v_mfma_f32_32x32x16_bf16 v[16:31], v[128:131], v[186:189], v[16:31]
	s_add_i32 m0, m0, 0x400
	v_lshl_add_u64 v[254:255], v[254:255], 0, s[82:83]
	global_load_lds_dwordx4 v[254:255], off
	ds_read_b64_tr_b16 v[186:187], v177 offset:0x1600
	ds_read_b64_tr_b16 v[188:189], v177 offset:0x1e00
	v_mfma_f32_32x32x16_bf16 v[80:95], v[194:197], v[108:111], v[80:95]
	s_waitcnt lgkmcnt(8)
	v_mfma_f32_32x32x16_bf16 v[16:31], v[132:135], v[190:193], v[16:31]
	s_add_i32 m0, m0, 0x3c00
	v_lshl_add_u64 v[254:255], v[254:255], 0, s[82:83]
	global_load_lds_dwordx4 v[254:255], off
	ds_read_b64_tr_b16 v[190:191], v160 offset:0x600
	ds_read_b64_tr_b16 v[192:193], v160 offset:0xe00
	ds_read_b64_tr_b16 v[144:145], v160 offset:0x1600
	ds_read_b64_tr_b16 v[146:147], v160 offset:0x1e00
	s_nop 0
	s_nop 0
	s_waitcnt lgkmcnt(6)
	v_mfma_f32_32x32x16_bf16 v[0:15], v[128:131], v[182:185], v[0:15]
	s_add_i32 m0, m0, 0x400
	v_lshl_add_u64 v[254:255], v[254:255], 0, s[82:83]
	global_load_lds_dwordx4 v[254:255], off
	v_mfma_f32_32x32x16_bf16 v[32:47], v[140:143], v[230:233], v[32:47]
	v_mov_b32_e32 v184, v172
	s_mov_b32 s26, s25
	v_mfma_f32_32x32x16_bf16 v[80:95], v[198:201], v[116:119], v[80:95]
	s_waitcnt lgkmcnt(4)
	v_mfma_f32_32x32x16_bf16 v[0:15], v[132:135], v[186:189], v[0:15]
	s_nop 10
	v_exp_f32_e32 v238, v82
	v_exp_f32_e32 v239, v83
	v_exp_f32_e32 v240, v84
	v_exp_f32_e32 v241, v85
	v_exp_f32_e32 v242, v86
	v_exp_f32_e32 v243, v87
	v_exp_f32_e32 v244, v88
	v_mfma_f32_32x32x16_bf16 v[32:47], v[136:139], v[234:237], v[32:47]
	v_exp_f32_e32 v236, v80
	v_exp_f32_e32 v237, v81
	v_exp_f32_e32 v245, v89
	v_exp_f32_e32 v246, v90
	v_exp_f32_e32 v247, v91
	v_exp_f32_e32 v248, v92
	v_exp_f32_e32 v249, v93
	v_exp_f32_e32 v250, v94
	v_exp_f32_e32 v251, v95
	v_cvt_pk_bf16_f32 v132, v236, v237
	v_cvt_pk_bf16_f32 v133, v238, v239
	v_cvt_pk_bf16_f32 v134, v240, v241
	v_cvt_pk_bf16_f32 v135, v242, v243
	v_mfma_f32_32x32x16_bf16 v[16:31], v[140:143], v[218:221], v[16:31]
	v_add_u32_e32 v234, s24, v217
	v_add_u32_e32 v235, s24, v151
	s_waitcnt lgkmcnt(2)
	v_mfma_f32_32x32x16_bf16 v[0:15], v[140:143], v[190:193], v[0:15]
	v_cvt_pk_bf16_f32 v140, v244, v245
	v_cvt_pk_bf16_f32 v141, v246, v247
	v_cvt_pk_bf16_f32 v142, v248, v249
	v_cvt_pk_bf16_f32 v143, v250, v251
	ds_write_b128 v181, v[132:135]
	ds_write_b128 v181, v[140:143] offset:1024
	s_waitcnt vmcnt(0) lgkmcnt(0)
	s_barrier
; #define WBAR(n) do { asm volatile("s_waitcnt vmcnt(" #n ") lgkmcnt(0)" ::: "memory"); __builtin_amdgcn_s_barrier(); asm volatile("" ::: "memory"); } while (0)
; #define WBAR(n) do { asm volatile("s_waitcnt vmcnt(" #n ") lgkmcnt(0)" ::: "memory"); __builtin_amdgcn_s_barrier(); asm volatile("" ::: "memory"); } while (0)
; template <int LD> ...
;     ...
;     DMA_TILE(j + 2, 1, v2);
;     STEP(0, pA, ownB0, ownB1, ownA0, ownA1);
;     WBAR(0);
;     { const int t = v0; v0 = v1; v1 = v2; v2 = t; }
;   }
	v_mfma_f32_32x32x16_bf16 v[16:31], v[136:139], v[222:225], v[16:31]
	v_mfma_f32_32x32x16_bf16 v[0:15], v[136:139], v[144:147], v[0:15]
	ds_read_b128 v[128:131], v171 offset:0x4000
	ds_read_b128 v[136:139], v171 offset:0x4400
	ds_read_b64_tr_b16 v[144:145], v234 offset:0
	ds_read_b64_tr_b16 v[146:147], v234 offset:0x800
	ds_read_b64_tr_b16 v[166:167], v234 offset:0x1000
	ds_read_b64_tr_b16 v[168:169], v234 offset:0x1800
	ds_read_b64_tr_b16 v[182:183], v235 offset:0
	s_nop 0
	v_xad_u32 v158, v184, v178, v173
	v_xad_u32 v159, v184, v174, v173
	v_xad_u32 v222, v184, v175, v173
	v_xad_u32 v223, v184, v176, v173
	ds_read_b64_tr_b16 v[184:185], v235 offset:0x800
	ds_read_b64_tr_b16 v[186:187], v235 offset:0x1000
	ds_read_b64_tr_b16 v[188:189], v235 offset:0x1800
	ds_read_b128 v[190:193], v158 offset:0
	ds_read_b128 v[194:197], v159 offset:0
	ds_read_b128 v[198:201], v222 offset:0
	ds_read_b128 v[218:221], v223 offset:0
	s_nop 0
	s_waitcnt lgkmcnt(3)
	v_mfma_f32_32x32x16_bf16 v[80:95], v[190:193], v[120:123], v[64:79]
	s_add_i32 s53, s53, 2
	v_mfma_f32_32x32x16_bf16 v[48:63], v[132:135], v[144:147], v[48:63]
	v_xor_b32_e32 v158, 0x80, v158
	ds_read_b128 v[144:147], v158 offset:0
	s_waitcnt lgkmcnt(3)
	v_mfma_f32_32x32x16_bf16 v[80:95], v[194:197], v[124:127], v[80:95]
	v_mfma_f32_32x32x16_bf16 v[48:63], v[140:143], v[166:169], v[48:63]
	v_xor_b32_e32 v159, 0x80, v159
	ds_read_b128 v[166:169], v159 offset:0
	v_xor_b32_e32 v222, 0x80, v222
	ds_read_b128 v[190:193], v222 offset:0
	v_xor_b32_e32 v223, 0x80, v223
	ds_read_b128 v[194:197], v223 offset:0
	ds_read_b64_tr_b16 v[222:223], v234 offset:0x200
	ds_read_b64_tr_b16 v[224:225], v234 offset:0xa00
	s_waitcnt lgkmcnt(7)
	v_mfma_f32_32x32x16_bf16 v[80:95], v[198:201], v[112:115], v[80:95]
	ds_read_b64_tr_b16 v[198:199], v234 offset:0x1200
	ds_read_b64_tr_b16 v[200:201], v234 offset:0x1a00
	ds_read_b64_tr_b16 v[226:227], v235 offset:0x200
	ds_read_b64_tr_b16 v[228:229], v235 offset:0xa00
	ds_read_b64_tr_b16 v[230:231], v235 offset:0x1200
	ds_read_b64_tr_b16 v[232:233], v235 offset:0x1a00
	s_waitcnt lgkmcnt(12)
	v_mfma_f32_32x32x16_bf16 v[80:95], v[218:221], v[100:103], v[80:95]
	v_mfma_f32_32x32x16_bf16 v[48:63], v[128:131], v[182:185], v[48:63]
	s_mov_b32 m0, s6
	v_lshl_add_u64 v[254:255], vcc, 0, v[152:153]
	v_lshl_add_u64 v[254:255], v[254:255], 0, s[90:91]
	global_load_lds_dwordx4 v[254:255], off
	ds_read_b64_tr_b16 v[182:183], v234 offset:0x400
	ds_read_b64_tr_b16 v[184:185], v234 offset:0xc00
	s_waitcnt lgkmcnt(8)
	v_mfma_f32_32x32x16_bf16 v[32:47], v[132:135], v[222:225], v[32:47]
	v_mfma_f32_32x32x16_bf16 v[80:95], v[144:147], v[96:99], v[80:95]
	s_mov_b32 m0, s7
	v_lshl_add_u64 v[254:255], vcc, 0, v[154:155]
	v_lshl_add_u64 v[254:255], v[254:255], 0, s[90:91]
	global_load_lds_dwordx4 v[254:255], off
	v_mfma_f32_32x32x16_bf16 v[48:63], v[136:139], v[186:189], v[48:63]
	ds_read_b64_tr_b16 v[186:187], v234 offset:0x1400
	ds_read_b64_tr_b16 v[188:189], v234 offset:0x1c00
	s_waitcnt lgkmcnt(8)
	v_mfma_f32_32x32x16_bf16 v[32:47], v[140:143], v[198:201], v[32:47]
	s_mov_b32 m0, s78
	s_mov_b64 s[26:27], 0xeb02000
	v_lshl_add_u64 v[254:255], vcc, 0, v[156:157]
	v_lshl_add_u64 v[254:255], v[254:255], 0, s[26:27]
	global_load_lds_dwordx4 v[254:255], off
	s_mov_b32 s26, s25
	s_add_u32 vcc_lo, vcc_lo, 0x200000
	s_addc_u32 vcc_hi, vcc_hi, 0
	ds_read_b64_tr_b16 v[198:199], v235 offset:0x400
	ds_read_b64_tr_b16 v[200:201], v235 offset:0xc00
	ds_read_b64_tr_b16 v[218:219], v235 offset:0x1400
	ds_read_b64_tr_b16 v[220:221], v235 offset:0x1c00
	s_nop 0
	ds_read_b64_tr_b16 v[144:145], v234 offset:0x600
	v_mfma_f32_32x32x16_bf16 v[80:95], v[166:169], v[104:107], v[80:95]
	ds_read_b64_tr_b16 v[146:147], v234 offset:0xe00
	ds_read_b64_tr_b16 v[166:167], v234 offset:0x1600
	s_waitcnt lgkmcnt(14)
	ds_read_b64_tr_b16 v[168:169], v234 offset:0x1e00
	s_waitcnt lgkmcnt(10)
	v_mfma_f32_32x32x16_bf16 v[16:31], v[132:135], v[182:185], v[16:31]
	s_add_i32 m0, s78, 0x400
	v_lshl_add_u64 v[254:255], v[254:255], 0, s[82:83]
	global_load_lds_dwordx4 v[254:255], off
	ds_read_b64_tr_b16 v[182:183], v235 offset:0x600
	ds_read_b64_tr_b16 v[184:185], v235 offset:0xe00
	v_mfma_f32_32x32x16_bf16 v[80:95], v[190:193], v[108:111], v[80:95]
	s_waitcnt lgkmcnt(10)
	v_mfma_f32_32x32x16_bf16 v[16:31], v[140:143], v[186:189], v[16:31]
	s_add_i32 m0, s78, 0x4000
	v_lshl_add_u64 v[254:255], v[254:255], 0, s[82:83]
	global_load_lds_dwordx4 v[254:255], off
	ds_read_b64_tr_b16 v[186:187], v235 offset:0x1600
	ds_read_b64_tr_b16 v[188:189], v235 offset:0x1e00
	s_nop 0
	s_nop 0
	s_waitcnt lgkmcnt(6)
	v_mfma_f32_32x32x16_bf16 v[0:15], v[132:135], v[144:147], v[0:15]
	s_add_i32 m0, s78, 0x4400
	v_lshl_add_u64 v[254:255], v[254:255], 0, s[82:83]
	global_load_lds_dwordx4 v[254:255], off
	v_add_f32_e32 v132, v170, v236
	v_add_f32_e32 v132, v237, v132
	v_add_f32_e32 v132, v238, v132
	v_add_f32_e32 v132, v239, v132
	v_add_f32_e32 v132, v240, v132
	v_add_f32_e32 v132, v241, v132
	v_add_f32_e32 v132, v242, v132
	v_mfma_f32_32x32x16_bf16 v[80:95], v[194:197], v[116:119], v[80:95]
	v_add_f32_e32 v132, v243, v132
	v_add_f32_e32 v132, v244, v132
	v_add_f32_e32 v132, v245, v132
	v_add_f32_e32 v132, v246, v132
	v_add_f32_e32 v132, v247, v132
	v_add_f32_e32 v132, v248, v132
	v_add_f32_e32 v132, v249, v132
	s_waitcnt lgkmcnt(4)
	v_mfma_f32_32x32x16_bf16 v[0:15], v[140:143], v[166:169], v[0:15]
	s_nop 3
	v_exp_f32_e32 v80, v80
	v_exp_f32_e32 v81, v81
	v_add_f32_e32 v132, v250, v132
	v_exp_f32_e32 v82, v82
	v_add_f32_e32 v132, v251, v132
	v_exp_f32_e32 v83, v83
	v_exp_f32_e32 v84, v84
	v_mfma_f32_32x32x16_bf16 v[32:47], v[128:131], v[226:229], v[32:47]
	v_add_f32_e32 v140, v132, v80
	v_exp_f32_e32 v85, v85
	v_exp_f32_e32 v86, v86
	v_exp_f32_e32 v87, v87
	v_exp_f32_e32 v88, v88
	v_exp_f32_e32 v89, v89
	v_exp_f32_e32 v90, v90
	v_mfma_f32_32x32x16_bf16 v[16:31], v[128:131], v[198:201], v[16:31]
	v_exp_f32_e32 v91, v91
	v_exp_f32_e32 v92, v92
	v_exp_f32_e32 v93, v93
	v_exp_f32_e32 v94, v94
	v_exp_f32_e32 v95, v95
	v_cvt_pk_bf16_f32 v132, v88, v89
	v_cvt_pk_bf16_f32 v133, v90, v91
	s_waitcnt lgkmcnt(2)
	v_mfma_f32_32x32x16_bf16 v[0:15], v[128:131], v[182:185], v[0:15]
	v_cvt_pk_bf16_f32 v128, v80, v81
	v_add_f32_e32 v80, v81, v140
	v_add_f32_e32 v80, v82, v80
	v_add_f32_e32 v80, v83, v80
	v_add_f32_e32 v80, v84, v80
	v_add_f32_e32 v80, v85, v80
	v_add_f32_e32 v80, v86, v80
	v_add_f32_e32 v80, v87, v80
	v_mfma_f32_32x32x16_bf16 v[32:47], v[136:139], v[230:233], v[32:47]
	v_add_f32_e32 v80, v88, v80
	v_add_f32_e32 v80, v89, v80
	v_add_f32_e32 v80, v90, v80
	v_cvt_pk_bf16_f32 v129, v82, v83
	v_cvt_pk_bf16_f32 v130, v84, v85
	v_cvt_pk_bf16_f32 v131, v86, v87
	v_add_f32_e32 v80, v91, v80
	v_mfma_f32_32x32x16_bf16 v[16:31], v[136:139], v[218:221], v[16:31]
	v_cvt_pk_bf16_f32 v134, v92, v93
	v_cvt_pk_bf16_f32 v135, v94, v95
	ds_write_b128 v180, v[128:131]
	ds_write_b128 v180, v[132:135] offset:1024
	v_add_f32_e32 v80, v92, v80
	s_waitcnt vmcnt(0) lgkmcnt(0)
	s_barrier
; #define WBAR(n) do { asm volatile("s_waitcnt vmcnt(" #n ") lgkmcnt(0)" ::: "memory"); __builtin_amdgcn_s_barrier(); asm volatile("" ::: "memory"); } while (0)
; #define WBAR(n) do { asm volatile("s_waitcnt vmcnt(" #n ") lgkmcnt(0)" ::: "memory"); __builtin_amdgcn_s_barrier(); asm volatile("" ::: "memory"); } while (0)
; template <int LD> ...
;     ...
;   for (int j = 1; j + 1 < NT; j += 2) {
;     DMA_TILE(j + 1, 0, v2);
;     STEP(1, pB, ownA0, ownA1, ownB0, ownB1);
;     WBAR(0);
;     { const int t = v0; v0 = v1; v1 = v2; v2 = t; }
;     DMA_TILE(j + 2, 1, v2);
;     STEP(0, pA, ownB0, ownB1, ownA0, ownA1);
;     WBAR(0);
;     { const int t = v0; v0 = v1; v1 = v2; v2 = t; }
;   }
	v_mfma_f32_32x32x16_bf16 v[0:15], v[136:139], v[186:189], v[0:15]
	v_add_f32_e32 v80, v93, v80
	v_add_f32_e32 v80, v94, v80
	v_add_f32_e32 v170, v95, v80
	s_cmp_ge_u32 s53, s51
	s_cbranch_scc0 .Lb_loopY

.LBB0_43:
	s_mov_b32 s41, s40
	v_lshl_add_u64 v[154:155], s[12:13], 0, v[160:161]
	s_mov_b64 s[24:25], 0xe941000
	v_lshl_add_u64 v[64:65], v[154:155], 0, s[24:25]
	s_mov_b32 m0, s16
	v_lshl_add_u64 v[156:157], s[12:13], 0, v[152:153]
	s_mov_b64 s[24:25], 0xe941400
	s_add_i32 s26, s14, s41
	global_load_lds_dwordx4 v[64:65], off
	v_lshl_add_u64 v[64:65], v[156:157], 0, s[24:25]
	s_mov_b32 m0, s26
	s_mov_b64 s[24:25], 0xe941480
	global_load_lds_dwordx4 v[64:65], off
	v_lshl_add_u64 v[64:65], v[156:157], 0, s[24:25]
	s_add_i32 m0, s26, 0x400
	s_mov_b32 s40, s17
	s_mov_b32 s17, s42
	global_load_lds_dwordx4 v[64:65], off
	v_mov_b32_e32 v64, v159
	v_mov_b32_e32 v96, v198
	v_add_u32_e32 v158, s17, v200
	ds_read_b64_tr_b16 v[146:147], v158 offset:0
	ds_read_b64_tr_b16 v[148:149], v158 offset:0x800
	ds_read_b64_tr_b16 v[180:181], v158 offset:0x1000
	ds_read_b64_tr_b16 v[182:183], v158 offset:0x1800
	ds_read_b64_tr_b16 v[184:185], v158 offset:0x2000
	ds_read_b64_tr_b16 v[186:187], v158 offset:0x2800
	v_xor_b32_e32 v65, v64, v166
	ds_read_b64_tr_b16 v[188:189], v158 offset:0x3000
	v_xor_b32_e32 v66, v64, v167
	v_xor_b32_e32 v67, v64, v168
	v_xor_b32_e32 v64, v64, v170
	v_lshl_add_u32 v72, v65, 4, v169
	ds_read_b64_tr_b16 v[190:191], v158 offset:0x3800
	v_lshl_add_u32 v73, v66, 4, v169
	v_lshl_add_u32 v145, v67, 4, v169
	v_lshl_add_u32 v150, v64, 4, v169
	ds_read_b128 v[64:67], v72 offset:16384
	ds_read_b128 v[68:71], v73 offset:16384
	ds_read_b128 v[172:175], v72 offset:20480
	ds_read_b128 v[176:179], v73 offset:20480
	v_mov_b32_e32 v97, v96
	v_mov_b32_e32 v98, v96
	v_mov_b32_e32 v99, v96
	v_mov_b32_e32 v100, v96
	v_mov_b32_e32 v101, v96
	v_mov_b32_e32 v102, v96
	v_mov_b32_e32 v103, v96
	v_mov_b32_e32 v104, v96
	v_mov_b32_e32 v105, v96
	v_mov_b32_e32 v106, v96
	v_mov_b32_e32 v107, v96
	v_mov_b32_e32 v108, v96
	v_mov_b32_e32 v109, v96
	v_mov_b32_e32 v110, v96
	v_mov_b32_e32 v111, v96
	s_waitcnt lgkmcnt(2)
	v_mfma_scale_f32_32x32x64_f8f6f4 v[80:95], v[64:71], v[112:119], v[96:111], v199, v199 op_sel_hi:[0,0,0]
	s_waitcnt lgkmcnt(0)
	v_mfma_scale_f32_32x32x64_f8f6f4 v[64:79], v[172:179], v[112:119], v[96:111], v199, v199 op_sel_hi:[0,0,0]
	ds_read_b128 v[96:99], v145 offset:16384
	ds_read_b128 v[100:103], v150 offset:16384
	ds_read_b128 v[104:107], v145 offset:20480
	ds_read_b128 v[108:111], v150 offset:20480
	ds_read_b64_tr_b16 v[172:173], v158 offset:0x200
	ds_read_b64_tr_b16 v[174:175], v158 offset:0xa00
	ds_read_b64_tr_b16 v[176:177], v158 offset:0x1200
	ds_read_b64_tr_b16 v[178:179], v158 offset:0x1a00
	ds_read_b64_tr_b16 v[192:193], v158 offset:0x2200
	s_nop 0
	v_mfma_f32_32x32x16_bf16 v[0:15], v[140:143], v[146:149], v[0:15]
	ds_read_b64_tr_b16 v[194:195], v158 offset:0x2a00
	ds_read_b64_tr_b16 v[212:213], v158 offset:0x3200
	ds_read_b64_tr_b16 v[214:215], v158 offset:0x3a00
	s_waitcnt lgkmcnt(10)
	v_mfma_scale_f32_32x32x64_f8f6f4 v[80:95], v[96:103], v[120:127], v[80:95], v199, v199 op_sel_hi:[0,0,0]
	s_waitcnt lgkmcnt(8)
	v_mfma_scale_f32_32x32x64_f8f6f4 v[64:79], v[104:111], v[120:127], v[64:79], v199, v199 op_sel_hi:[0,0,0]
	s_mov_b64 s[24:25], 0xe9e1000
	v_mfma_f32_32x32x16_bf16 v[0:15], v[136:139], v[180:183], v[0:15]
	v_exp_f32_e32 v171, v80
	ds_read_b64_tr_b16 v[96:97], v158 offset:0x400
	v_exp_f32_e32 v180, v81
	ds_read_b64_tr_b16 v[98:99], v158 offset:0xc00
	v_exp_f32_e32 v181, v82
	ds_read_b64_tr_b16 v[100:101], v158 offset:0x1400
	v_exp_f32_e32 v182, v83
	ds_read_b64_tr_b16 v[102:103], v158 offset:0x1c00
	v_add_f32_e32 v80, v144, v171
	v_exp_f32_e32 v183, v84
	v_mfma_f32_32x32x16_bf16 v[0:15], v[132:135], v[184:187], v[0:15]
	ds_read_b64_tr_b16 v[104:105], v158 offset:0x2400
	v_add_f32_e32 v80, v180, v80
	v_exp_f32_e32 v184, v85
	ds_read_b64_tr_b16 v[106:107], v158 offset:0x2c00
	v_add_f32_e32 v80, v181, v80
	v_exp_f32_e32 v185, v86
	ds_read_b64_tr_b16 v[108:109], v158 offset:0x3400
	v_add_f32_e32 v80, v182, v80
	v_exp_f32_e32 v186, v87
	s_waitcnt lgkmcnt(14)
	ds_read_b64_tr_b16 v[110:111], v158 offset:0x3c00
	v_add_f32_e32 v80, v183, v80
	s_nop 7
	v_add_f32_e32 v80, v184, v80
	v_add_f32_e32 v80, v185, v80
	v_add_f32_e32 v187, v186, v80
	s_waitcnt lgkmcnt(14)
	ds_read_b64_tr_b16 v[80:81], v158 offset:0x600
	s_waitcnt lgkmcnt(14)
	ds_read_b64_tr_b16 v[82:83], v158 offset:0xe00
	s_waitcnt lgkmcnt(14)
	ds_read_b64_tr_b16 v[84:85], v158 offset:0x1600
	s_waitcnt lgkmcnt(14)
	ds_read_b64_tr_b16 v[86:87], v158 offset:0x1e00
	s_waitcnt lgkmcnt(14)
	ds_read_b64_tr_b16 v[148:149], v158 offset:0x2600
	v_exp_f32_e32 v88, v88
	s_waitcnt lgkmcnt(14)
	ds_read_b64_tr_b16 v[150:151], v158 offset:0x2e00
	v_exp_f32_e32 v89, v89
	s_waitcnt lgkmcnt(14)
	ds_read_b64_tr_b16 v[144:145], v158 offset:0x3600
	v_exp_f32_e32 v90, v90
	s_waitcnt lgkmcnt(14)
	ds_read_b64_tr_b16 v[146:147], v158 offset:0x3e00
	v_exp_f32_e32 v91, v91
	v_mfma_f32_32x32x16_bf16 v[16:31], v[140:143], v[172:175], v[16:31]
	v_add_f32_e32 v172, v88, v187
	v_exp_f32_e32 v92, v92
	v_add_f32_e32 v172, v89, v172
	v_exp_f32_e32 v93, v93
	v_add_f32_e32 v172, v90, v172
	v_exp_f32_e32 v94, v94
	s_waitcnt lgkmcnt(6)
	v_mfma_f32_32x32x16_bf16 v[48:63], v[140:143], v[80:83], v[48:63]
	v_add_f32_e32 v172, v91, v172
	v_exp_f32_e32 v95, v95
	v_add_f32_e32 v172, v92, v172
	v_exp_f32_e32 v64, v64
	v_add_f32_e32 v172, v93, v172
	v_add_f32_e32 v172, v94, v172
	v_add_f32_e32 v172, v95, v172
	v_mfma_f32_32x32x16_bf16 v[32:47], v[140:143], v[96:99], v[32:47]
	v_exp_f32_e32 v97, v65
	v_add_f32_e32 v96, v64, v172
	v_exp_f32_e32 v98, v67
	v_exp_f32_e32 v99, v68
	v_add_f32_e32 v65, v97, v96
	v_exp_f32_e32 v96, v66
	v_exp_f32_e32 v68, v74
	s_waitcnt lgkmcnt(4)
	v_mfma_f32_32x32x16_bf16 v[48:63], v[136:139], v[84:87], v[48:63]
	s_waitcnt vmcnt(0) lgkmcnt(0)
	s_barrier
	s_mov_b32 m0, s15
	s_add_i32 s26, s14, s42
	v_add_f32_e32 v65, v96, v65
	v_add_f32_e32 v65, v98, v65
	v_mfma_f32_32x32x16_bf16 v[32:47], v[136:139], v[100:103], v[32:47]
	v_exp_f32_e32 v100, v69
	v_exp_f32_e32 v69, v75
	v_lshl_add_u64 v[74:75], v[154:155], 0, s[24:25]
	s_mov_b64 s[24:25], 0xe9e1400
	v_exp_f32_e32 v101, v70
	global_load_lds_dwordx4 v[74:75], off
	v_lshl_add_u64 v[74:75], v[156:157], 0, s[24:25]
	s_mov_b32 m0, s26
	s_mov_b64 s[24:25], 0xe9e1480
	v_exp_f32_e32 v102, v71
	global_load_lds_dwordx4 v[74:75], off
	v_lshl_add_u64 v[74:75], v[156:157], 0, s[24:25]
	s_add_i32 m0, s26, 0x400
	v_add_f32_e32 v65, v99, v65
	v_exp_f32_e32 v66, v72
	global_load_lds_dwordx4 v[74:75], off
	v_add_f32_e32 v65, v100, v65
	v_mfma_f32_32x32x16_bf16 v[48:63], v[132:135], v[148:151], v[48:63]
	v_exp_f32_e32 v67, v73
	v_cvt_pk_bf16_f32 v148, v64, v97
	v_mov_b32_e32 v64, v159
	v_add_f32_e32 v65, v101, v65
	v_add_f32_e32 v65, v102, v65
	v_exp_f32_e32 v70, v76
	v_exp_f32_e32 v71, v77
	v_xor_b32_e32 v74, v64, v166
	v_xor_b32_e32 v75, v64, v167
	v_xor_b32_e32 v76, v64, v168
	v_xor_b32_e32 v77, v64, v170
	v_mov_b32_e32 v64, v198
	v_mfma_f32_32x32x16_bf16 v[16:31], v[136:139], v[176:179], v[16:31]
	v_add_f32_e32 v65, v66, v65
	v_add_u32_e32 v196, s40, v200
	ds_read_b64_tr_b16 v[154:155], v196 offset:0
	v_add_f32_e32 v65, v67, v65
	ds_read_b64_tr_b16 v[156:157], v196 offset:0x800
	v_exp_f32_e32 v72, v78
	v_cvt_pk_bf16_f32 v136, v171, v180
	v_cvt_pk_bf16_f32 v137, v181, v182
	v_add_f32_e32 v65, v68, v65
	ds_read_b64_tr_b16 v[180:181], v196 offset:0x1000
	v_exp_f32_e32 v73, v79
	v_cvt_pk_bf16_f32 v138, v183, v184
	v_add_f32_e32 v65, v69, v65
	ds_read_b64_tr_b16 v[182:183], v196 offset:0x1800
	v_cvt_pk_bf16_f32 v139, v185, v186
	v_add_f32_e32 v65, v70, v65
	ds_read_b64_tr_b16 v[184:185], v196 offset:0x2000
	v_mfma_f32_32x32x16_bf16 v[0:15], v[128:131], v[188:191], v[0:15]
	v_add_f32_e32 v65, v71, v65
	ds_read_b64_tr_b16 v[186:187], v196 offset:0x2800
	v_add_f32_e32 v65, v72, v65
	ds_read_b64_tr_b16 v[188:189], v196 offset:0x3000
	v_add_f32_e32 v171, v73, v65
	v_lshl_add_u32 v65, v74, 4, v169
	ds_read_b64_tr_b16 v[190:191], v196 offset:0x3800
	v_mfma_f32_32x32x16_bf16 v[32:47], v[132:135], v[104:107], v[32:47]
	v_mov_b32_e32 v74, v64
	v_mov_b32_e32 v78, v64
	v_mov_b32_e32 v79, v64
	v_cvt_pk_bf16_f32 v140, v88, v89
	v_cvt_pk_bf16_f32 v141, v90, v91
	v_cvt_pk_bf16_f32 v142, v92, v93
	v_cvt_pk_bf16_f32 v143, v94, v95
	v_mfma_f32_32x32x16_bf16 v[16:31], v[132:135], v[192:195], v[16:31]
	v_cvt_pk_bf16_f32 v132, v66, v67
	v_lshl_add_u32 v66, v75, 4, v169
	ds_read_b128 v[80:83], v65
	ds_read_b128 v[84:87], v66
	ds_read_b128 v[172:175], v65 offset:4096
	ds_read_b128 v[176:179], v66 offset:4096
	v_cvt_pk_bf16_f32 v133, v68, v69
	v_cvt_pk_bf16_f32 v134, v70, v71
	v_cvt_pk_bf16_f32 v135, v72, v73
	v_lshl_add_u32 v192, v76, 4, v169
	v_lshl_add_u32 v193, v77, 4, v169
	v_mov_b32_e32 v65, v64
	v_mov_b32_e32 v66, v64
	v_mov_b32_e32 v67, v64
	v_mov_b32_e32 v68, v64
	v_mov_b32_e32 v69, v64
	v_mov_b32_e32 v70, v64
	v_mov_b32_e32 v71, v64
	v_mov_b32_e32 v72, v64
	v_mov_b32_e32 v73, v64
	v_mov_b32_e32 v75, v64
	v_mov_b32_e32 v76, v64
	v_mov_b32_e32 v77, v64
	v_mfma_f32_32x32x16_bf16 v[32:47], v[128:131], v[108:111], v[32:47]
	v_cvt_pk_bf16_f32 v149, v96, v98
	v_cvt_pk_bf16_f32 v150, v99, v100
	v_cvt_pk_bf16_f32 v151, v101, v102
	s_waitcnt lgkmcnt(2)
	v_mfma_scale_f32_32x32x64_f8f6f4 v[96:111], v[80:87], v[112:119], v[64:79], v199, v199 op_sel_hi:[0,0,0]
	s_waitcnt lgkmcnt(0)
	v_mfma_scale_f32_32x32x64_f8f6f4 v[80:95], v[172:179], v[112:119], v[64:79], v199, v199 op_sel_hi:[0,0,0]
	ds_read_b128 v[64:67], v192
	ds_read_b128 v[68:71], v193
	ds_read_b128 v[72:75], v192 offset:4096
	ds_read_b128 v[76:79], v193 offset:4096
	ds_read_b64_tr_b16 v[172:173], v196 offset:0x200
	ds_read_b64_tr_b16 v[174:175], v196 offset:0xa00
	ds_read_b64_tr_b16 v[176:177], v196 offset:0x1200
	ds_read_b64_tr_b16 v[178:179], v196 offset:0x1a00
	ds_read_b64_tr_b16 v[192:193], v196 offset:0x2200
	s_nop 0
	v_mfma_f32_32x32x16_bf16 v[0:15], v[136:139], v[154:157], v[0:15]
	ds_read_b64_tr_b16 v[194:195], v196 offset:0x2a00
	s_add_u32 s12, s12, 0x140000
	s_addc_u32 s13, s13, 0
	s_add_i32 s39, s39, 2
	s_cmp_ge_u32 s39, s38
	s_mov_b32 s42, s41
	v_mfma_f32_32x32x16_bf16 v[16:31], v[128:131], v[212:215], v[16:31]
	ds_read_b64_tr_b16 v[212:213], v196 offset:0x3200
	ds_read_b64_tr_b16 v[214:215], v196 offset:0x3a00
	s_waitcnt lgkmcnt(10)
	v_mfma_scale_f32_32x32x64_f8f6f4 v[96:111], v[64:71], v[120:127], v[96:111], v199, v199 op_sel_hi:[0,0,0]
	s_waitcnt lgkmcnt(8)
	v_mfma_scale_f32_32x32x64_f8f6f4 v[80:95], v[72:79], v[120:127], v[80:95], v199, v199 op_sel_hi:[0,0,0]
	ds_read_b64_tr_b16 v[64:65], v196 offset:0x400
	v_mfma_f32_32x32x16_bf16 v[0:15], v[140:143], v[180:183], v[0:15]
	v_exp_f32_e32 v180, v96
	ds_read_b64_tr_b16 v[66:67], v196 offset:0xc00
	v_exp_f32_e32 v181, v98
	ds_read_b64_tr_b16 v[68:69], v196 offset:0x1400
	v_add_f32_e32 v96, v171, v180
	v_exp_f32_e32 v171, v97
	v_exp_f32_e32 v182, v99
	ds_read_b64_tr_b16 v[70:71], v196 offset:0x1c00
	v_exp_f32_e32 v183, v100
	v_mfma_f32_32x32x16_bf16 v[0:15], v[148:151], v[184:187], v[0:15]
	ds_read_b64_tr_b16 v[72:73], v196 offset:0x2400
	v_add_f32_e32 v96, v171, v96
	v_exp_f32_e32 v184, v101
	ds_read_b64_tr_b16 v[74:75], v196 offset:0x2c00
	v_add_f32_e32 v96, v181, v96
	v_exp_f32_e32 v185, v102
	ds_read_b64_tr_b16 v[76:77], v196 offset:0x3400
	v_add_f32_e32 v96, v182, v96
	v_exp_f32_e32 v186, v103
	s_waitcnt lgkmcnt(14)
	ds_read_b64_tr_b16 v[78:79], v196 offset:0x3c00
	v_add_f32_e32 v96, v183, v96
	s_nop 7
	v_add_f32_e32 v96, v184, v96
	v_add_f32_e32 v96, v185, v96
	v_add_f32_e32 v187, v186, v96
	s_waitcnt lgkmcnt(14)
	ds_read_b64_tr_b16 v[96:97], v196 offset:0x600
	v_mfma_f32_32x32x16_bf16 v[48:63], v[128:131], v[144:147], v[48:63]
	s_waitcnt lgkmcnt(14)
	ds_read_b64_tr_b16 v[98:99], v196 offset:0xe00
	s_waitcnt lgkmcnt(14)
	ds_read_b64_tr_b16 v[100:101], v196 offset:0x1600
	s_waitcnt lgkmcnt(14)
	ds_read_b64_tr_b16 v[102:103], v196 offset:0x1e00
	s_waitcnt lgkmcnt(14)
	ds_read_b64_tr_b16 v[154:155], v196 offset:0x2600
	s_waitcnt lgkmcnt(14)
	ds_read_b64_tr_b16 v[156:157], v196 offset:0x2e00
	v_exp_f32_e32 v104, v104
	v_exp_f32_e32 v105, v105
	v_mfma_f32_32x32x16_bf16 v[16:31], v[136:139], v[172:175], v[16:31]
	s_waitcnt lgkmcnt(14)
	ds_read_b64_tr_b16 v[172:173], v196 offset:0x3600
	s_waitcnt lgkmcnt(14)
	ds_read_b64_tr_b16 v[174:175], v196 offset:0x3e00
	v_exp_f32_e32 v106, v106
	v_exp_f32_e32 v107, v107
	v_exp_f32_e32 v108, v108
	v_exp_f32_e32 v109, v109
	s_waitcnt lgkmcnt(14)
	v_mfma_f32_32x32x16_bf16 v[32:47], v[136:139], v[64:67], v[32:47]
	v_exp_f32_e32 v110, v110
	v_exp_f32_e32 v111, v111
	v_exp_f32_e32 v64, v80
	v_exp_f32_e32 v66, v81
	v_exp_f32_e32 v67, v82
	v_exp_f32_e32 v80, v91
	v_exp_f32_e32 v81, v92
	s_waitcnt lgkmcnt(6)
	v_mfma_f32_32x32x16_bf16 v[48:63], v[136:139], v[96:99], v[48:63]
	v_exp_f32_e32 v82, v93
	s_waitcnt vmcnt(0) lgkmcnt(0)
	s_barrier
; #define WBAR(n) do { asm volatile("s_waitcnt vmcnt(" #n ") lgkmcnt(0)" ::: "memory"); __builtin_amdgcn_s_barrier(); asm volatile("" ::: "memory"); } while (0)
; #define TRW(T, n) asm volatile("s_waitcnt lgkmcnt(" #n ")" : "+v"(T[0]), "+v"(T[1]), "+v"(T[2]), "+v"(T[3]), "+v"(T[4]), "+v"(T[5]), "+v"(T[6]), "+v"(T[7]) :: "memory")
; #define WBAR(n) do { asm volatile("s_waitcnt vmcnt(" #n ") lgkmcnt(0)" ::: "memory"); __builtin_amdgcn_s_barrier(); asm volatile("" ::: "memory"); } while (0)
; #define TRA(T, D0, vb_) do { T[0] = tr_read<v_rd_off(D0, 0, 0)>(vb_); T[1] = tr_read<v_rd_off(D0, 0, 1)>(vb_); T[2] = tr_read<v_rd_off(D0, 1, 0)>(vb_); T[3] = tr_read<v_rd_off(D0, 1, 1)>(vb_); \
;     T[4] = tr_read<v_rd_off(D0, 2, 0)>(vb_); T[5] = tr_read<v_rd_off(D0, 2, 1)>(vb_); T[6] = tr_read<v_rd_off(D0, 3, 0)>(vb_); T[7] = tr_read<v_rd_off(D0, 3, 1)>(vb_); } while (0)
; #define TRW(T, n) asm volatile("s_waitcnt lgkmcnt(" #n ")" : "+v"(T[0]), "+v"(T[1]), "+v"(T[2]), "+v"(T[3]), "+v"(T[4]), "+v"(T[5]), "+v"(T[6]), "+v"(T[7]) :: "memory")
; template <int LD, class Epi> ...
;     ...
;   for (int j = 1; j + 1 < NT; j += 2) {
;     DMA_TILE(j + 1, 0, v2);
;     STEP(16384);
;     WBAR(0);
;     { const int t = v0; v0 = v1; v1 = v2; v2 = t; }
;     DMA_TILE(j + 2, 1, v2);
;     STEP(0);
;     WBAR(0);
;     { const int t = v0; v0 = v1; v1 = v2; v2 = t; }
;   }
;   STEP(16384);
;   { const int vb_ = vb0 + v1;
;     TRA(trA, 0, vb_); TRW(trA, 0); TRA(trB, 1, vb_);
	v_cvt_pk_bf16_f32 v136, v104, v105
	v_cvt_pk_bf16_f32 v137, v106, v107
	v_cvt_pk_bf16_f32 v138, v108, v109
	v_mfma_f32_32x32x16_bf16 v[16:31], v[140:143], v[176:179], v[16:31]
	v_add_f32_e32 v176, v104, v187
	v_add_f32_e32 v176, v105, v176
	v_add_f32_e32 v176, v106, v176
	v_add_f32_e32 v176, v107, v176
	v_add_f32_e32 v176, v108, v176
	v_add_f32_e32 v176, v109, v176
	v_add_f32_e32 v176, v110, v176
	v_mfma_f32_32x32x16_bf16 v[32:47], v[140:143], v[68:71], v[32:47]
	v_add_f32_e32 v176, v111, v176
	v_exp_f32_e32 v68, v83
	v_add_f32_e32 v65, v64, v176
	v_exp_f32_e32 v69, v84
	v_add_f32_e32 v65, v66, v65
	v_exp_f32_e32 v70, v85
	v_add_f32_e32 v65, v67, v65
	v_mfma_f32_32x32x16_bf16 v[48:63], v[140:143], v[100:103], v[48:63]
	v_exp_f32_e32 v71, v86
	v_add_f32_e32 v65, v68, v65
	v_add_f32_e32 v65, v69, v65
	v_add_f32_e32 v65, v70, v65
	v_add_f32_e32 v65, v71, v65
	v_exp_f32_e32 v83, v94
	v_exp_f32_e32 v84, v95
	v_mfma_f32_32x32x16_bf16 v[16:31], v[148:151], v[192:195], v[16:31]
	v_cvt_pk_bf16_f32 v140, v180, v171
	v_cvt_pk_bf16_f32 v141, v181, v182
	v_cvt_pk_bf16_f32 v142, v183, v184
	v_cvt_pk_bf16_f32 v143, v185, v186
	v_cvt_pk_bf16_f32 v139, v110, v111
	v_cvt_pk_bf16_f32 v130, v81, v82
	v_cvt_pk_bf16_f32 v131, v83, v84
	v_mfma_f32_32x32x16_bf16 v[32:47], v[148:151], v[72:75], v[32:47]
	v_exp_f32_e32 v72, v87
	v_exp_f32_e32 v73, v88
	v_exp_f32_e32 v74, v89
	v_exp_f32_e32 v75, v90
	v_add_f32_e32 v65, v72, v65
	v_add_f32_e32 v65, v73, v65
	v_add_f32_e32 v65, v74, v65
	v_mfma_f32_32x32x16_bf16 v[48:63], v[148:151], v[154:157], v[48:63]
	v_add_f32_e32 v65, v75, v65
	v_add_f32_e32 v65, v80, v65
	v_add_f32_e32 v65, v81, v65
	v_add_f32_e32 v65, v82, v65
	v_add_f32_e32 v65, v83, v65
	v_add_f32_e32 v144, v84, v65
	v_cvt_pk_bf16_f32 v128, v73, v74
	v_mfma_f32_32x32x16_bf16 v[0:15], v[132:135], v[188:191], v[0:15]
	v_cvt_pk_bf16_f32 v129, v75, v80
	v_mfma_f32_32x32x16_bf16 v[16:31], v[132:135], v[212:215], v[16:31]
	v_mfma_f32_32x32x16_bf16 v[32:47], v[132:135], v[76:79], v[32:47]
	v_mfma_f32_32x32x16_bf16 v[48:63], v[132:135], v[172:175], v[48:63]
	v_cvt_pk_bf16_f32 v132, v64, v66
	v_cvt_pk_bf16_f32 v133, v67, v68
	v_cvt_pk_bf16_f32 v134, v69, v70
	v_cvt_pk_bf16_f32 v135, v71, v72
	s_cbranch_scc0 .LBB0_43
	v_mov_b32_e32 v96, v198
	v_add_u32_e32 v145, s41, v200
	ds_read_b64_tr_b16 v[154:155], v145 offset:0
	ds_read_b64_tr_b16 v[156:157], v145 offset:0x800
	v_xor_b32_e32 v64, v159, v166
	v_xor_b32_e32 v65, v159, v167
	v_xor_b32_e32 v66, v159, v168
	v_xor_b32_e32 v67, v159, v170
	ds_read_b64_tr_b16 v[166:167], v145 offset:0x1000
	v_lshl_add_u32 v68, v64, 4, v169
	v_lshl_add_u32 v72, v65, 4, v169
	v_lshl_add_u32 v159, v66, 4, v169
	v_lshl_add_u32 v160, v67, 4, v169
	ds_read_b64_tr_b16 v[168:169], v145 offset:0x1800
	ds_read_b64_tr_b16 v[170:171], v145 offset:0x2000
	ds_read_b64_tr_b16 v[172:173], v145 offset:0x2800
	ds_read_b64_tr_b16 v[174:175], v145 offset:0x3000
	ds_read_b64_tr_b16 v[176:177], v145 offset:0x3800
	ds_read_b128 v[64:67], v68 offset:16384
	ds_read_b128 v[146:149], v68 offset:20480
	ds_read_b128 v[68:71], v72 offset:16384
	ds_read_b128 v[150:153], v72 offset:20480
	v_mov_b32_e32 v97, v96
	v_mov_b32_e32 v98, v96
	v_mov_b32_e32 v99, v96
	v_mov_b32_e32 v100, v96
	v_mov_b32_e32 v101, v96
	v_mov_b32_e32 v102, v96
	v_mov_b32_e32 v103, v96
	v_mov_b32_e32 v104, v96
	v_mov_b32_e32 v105, v96
	v_mov_b32_e32 v106, v96
	v_mov_b32_e32 v107, v96
	v_mov_b32_e32 v108, v96
	v_mov_b32_e32 v109, v96
	v_mov_b32_e32 v110, v96
	v_mov_b32_e32 v111, v96
	s_waitcnt lgkmcnt(0)
	v_mfma_scale_f32_32x32x64_f8f6f4 v[80:95], v[64:71], v[112:119], v[96:111], v199, v199 op_sel_hi:[0,0,0]
	v_mfma_scale_f32_32x32x64_f8f6f4 v[64:79], v[146:153], v[112:119], v[96:111], v199, v199 op_sel_hi:[0,0,0]
	ds_read_b128 v[96:99], v159 offset:16384
	ds_read_b128 v[104:107], v159 offset:20480
	ds_read_b128 v[100:103], v160 offset:16384
	ds_read_b128 v[108:111], v160 offset:20480
	s_waitcnt lgkmcnt(0)
	ds_read_b64_tr_b16 v[112:113], v145 offset:0x200
	ds_read_b64_tr_b16 v[114:115], v145 offset:0xa00
	ds_read_b64_tr_b16 v[116:117], v145 offset:0x1200
	ds_read_b64_tr_b16 v[118:119], v145 offset:0x1a00
	ds_read_b64_tr_b16 v[146:147], v145 offset:0x2200
	ds_read_b64_tr_b16 v[148:149], v145 offset:0x2a00
	ds_read_b64_tr_b16 v[150:151], v145 offset:0x3200
	ds_read_b64_tr_b16 v[152:153], v145 offset:0x3a00
	s_waitcnt lgkmcnt(0)
	v_mfma_scale_f32_32x32x64_f8f6f4 v[80:95], v[96:103], v[120:127], v[80:95], v199, v199 op_sel_hi:[0,0,0]
	v_mfma_scale_f32_32x32x64_f8f6f4 v[64:79], v[104:111], v[120:127], v[64:79], v199, v199 op_sel_hi:[0,0,0]
	v_mfma_f32_32x32x16_bf16 v[0:15], v[140:143], v[154:157], v[0:15]
	s_waitcnt lgkmcnt(0)
	ds_read_b64_tr_b16 v[96:97], v145 offset:0x400
	ds_read_b64_tr_b16 v[98:99], v145 offset:0xc00
	ds_read_b64_tr_b16 v[100:101], v145 offset:0x1400
	ds_read_b64_tr_b16 v[102:103], v145 offset:0x1c00
	ds_read_b64_tr_b16 v[104:105], v145 offset:0x2400
	ds_read_b64_tr_b16 v[106:107], v145 offset:0x2c00
	ds_read_b64_tr_b16 v[108:109], v145 offset:0x3400
	ds_read_b64_tr_b16 v[110:111], v145 offset:0x3c00
	s_nop 7
	v_mfma_f32_32x32x16_bf16 v[0:15], v[136:139], v[166:169], v[0:15]
	s_waitcnt lgkmcnt(0)
	v_exp_f32_e32 v120, v84
	v_exp_f32_e32 v121, v85
	v_exp_f32_e32 v122, v86
	v_exp_f32_e32 v123, v87
	v_exp_f32_e32 v127, v67
	v_exp_f32_e32 v124, v92
	v_mfma_f32_32x32x16_bf16 v[32:47], v[140:143], v[96:99], v[32:47]
	ds_read_b64_tr_b16 v[96:97], v145 offset:0x600
	ds_read_b64_tr_b16 v[98:99], v145 offset:0xe00
	v_cvt_pk_bf16_f32 v67, v122, v123
	v_exp_f32_e32 v125, v93
	v_exp_f32_e32 v126, v94
	v_mfma_f32_32x32x16_bf16 v[32:47], v[136:139], v[100:103], v[32:47]
	ds_read_b64_tr_b16 v[100:101], v145 offset:0x1600
	ds_read_b64_tr_b16 v[102:103], v145 offset:0x1e00
	v_mfma_f32_32x32x16_bf16 v[32:47], v[132:135], v[104:107], v[32:47]
	ds_read_b64_tr_b16 v[104:105], v145 offset:0x2600
	ds_read_b64_tr_b16 v[106:107], v145 offset:0x2e00
	v_mfma_f32_32x32x16_bf16 v[16:31], v[140:143], v[112:115], v[16:31]
	ds_read_b64_tr_b16 v[112:113], v145 offset:0x3600
	ds_read_b64_tr_b16 v[114:115], v145 offset:0x3e00
	s_nop 0
	s_waitcnt lgkmcnt(0)
; __device__ __forceinline__ int fresh_lane() { int l; asm volatile("v_mbcnt_lo_u32_b32 %0, -1, 0\n\tv_mbcnt_hi_u32_b32 %0, -1, %0" : "=v"(l)); return l; }
; #define WBAR(n) do { asm volatile("s_waitcnt vmcnt(" #n ") lgkmcnt(0)" ::: "memory"); __builtin_amdgcn_s_barrier(); asm volatile("" ::: "memory"); } while (0)
; #define TRW(T, n) asm volatile("s_waitcnt lgkmcnt(" #n ")" : "+v"(T[0]), "+v"(T[1]), "+v"(T[2]), "+v"(T[3]), "+v"(T[4]), "+v"(T[5]), "+v"(T[6]), "+v"(T[7]) :: "memory")
; #define MB(od, T, o0, o1, t0, t1) do { od = __builtin_amdgcn_mfma_f32_32x32x16_bf16(o0, PKV(T[0], T[1]), od, 0, 0, 0); od = __builtin_amdgcn_mfma_f32_32x32x16_bf16(o1, PKV(T[2], T[3]), od, 0, 0, 0); \
;     od = __builtin_amdgcn_mfma_f32_32x32x16_bf16(t0, PKV(T[4], T[5]), od, 0, 0, 0); od = __builtin_amdgcn_mfma_f32_32x32x16_bf16(t1, PKV(T[6], T[7]), od, 0, 0, 0); } while (0)
; #define WBAR(n) do { asm volatile("s_waitcnt vmcnt(" #n ") lgkmcnt(0)" ::: "memory"); __builtin_amdgcn_s_barrier(); asm volatile("" ::: "memory"); } while (0)
; #define TRA(T, D0, vb_) do { T[0] = tr_read<v_rd_off(D0, 0, 0)>(vb_); T[1] = tr_read<v_rd_off(D0, 0, 1)>(vb_); T[2] = tr_read<v_rd_off(D0, 1, 0)>(vb_); T[3] = tr_read<v_rd_off(D0, 1, 1)>(vb_); \
;     T[4] = tr_read<v_rd_off(D0, 2, 0)>(vb_); T[5] = tr_read<v_rd_off(D0, 2, 1)>(vb_); T[6] = tr_read<v_rd_off(D0, 3, 0)>(vb_); T[7] = tr_read<v_rd_off(D0, 3, 1)>(vb_); } while (0)
; #define TRW(T, n) asm volatile("s_waitcnt lgkmcnt(" #n ")" : "+v"(T[0]), "+v"(T[1]), "+v"(T[2]), "+v"(T[3]), "+v"(T[4]), "+v"(T[5]), "+v"(T[6]), "+v"(T[7]) :: "memory")
; template <int LD, class Epi> ...
;     ...
;   { const int vb_ = vb0 + v1;
;     TRA(trA, 0, vb_); TRW(trA, 0); TRA(trB, 1, vb_);
;     MB(o[0], trA); TRW(trB, 0); TRA(trA, 2, vb_);
;     MB(o[1], trB); TRW(trA, 0); TRA(trB, 3, vb_);
;     MB(o[2], trA); TRW(trB, 0);
;     MB(o[3], trB); }
;   WBAR(0);
;     ...
;   { auto rr = __builtin_amdgcn_permlane32_swap(__float_as_uint(lsum), __float_as_uint(lsum), false, false);
;     lsum = __uint_as_float(rr[0]) + __uint_as_float(rr[1]); }
;   const int lane2 = fresh_lane(), r32e = lane2 & 31, hie = lane2 >> 5;
;   if (hie == 0) li_l[r32e] = lsum; asm volatile("s_waitcnt lgkmcnt(0)" ::: "memory");
	s_nop 0
	v_mfma_f32_32x32x16_bf16 v[48:63], v[140:143], v[96:99], v[48:63]
	v_mfma_f32_32x32x16_bf16 v[0:15], v[132:135], v[170:173], v[0:15]
	v_mfma_f32_32x32x16_bf16 v[48:63], v[136:139], v[100:103], v[48:63]
	v_exp_f32_e32 v100, v88
	v_exp_f32_e32 v101, v89
	v_exp_f32_e32 v102, v90
	v_exp_f32_e32 v103, v91
	v_mfma_f32_32x32x16_bf16 v[16:31], v[136:139], v[116:119], v[16:31]
	v_exp_f32_e32 v116, v80
	v_exp_f32_e32 v117, v81
	v_exp_f32_e32 v118, v82
	v_exp_f32_e32 v119, v83
	v_exp_f32_e32 v136, v76
	v_mfma_f32_32x32x16_bf16 v[0:15], v[128:131], v[174:177], v[0:15]
	v_mfma_f32_32x32x16_bf16 v[32:47], v[128:131], v[108:111], v[32:47]
	v_exp_f32_e32 v108, v70
	v_exp_f32_e32 v109, v71
	ds_read_b64_tr_b16 v[70:71], v158 offset:0
	v_exp_f32_e32 v110, v72
	v_exp_f32_e32 v111, v73
	ds_read_b64_tr_b16 v[72:73], v158 offset:0x800
	ds_read_b64_tr_b16 v[80:81], v158 offset:0x1000
	v_mfma_f32_32x32x16_bf16 v[48:63], v[132:135], v[104:107], v[48:63]
	v_exp_f32_e32 v105, v64
	v_exp_f32_e32 v106, v65
	v_exp_f32_e32 v107, v66
	v_cvt_pk_bf16_f32 v64, v116, v117
	v_cvt_pk_bf16_f32 v65, v118, v119
	v_cvt_pk_bf16_f32 v66, v120, v121
	ds_read_b64_tr_b16 v[82:83], v158 offset:0x1800
	ds_read_b64_tr_b16 v[84:85], v158 offset:0x2000
	ds_read_b64_tr_b16 v[86:87], v158 offset:0x2800
	ds_read_b64_tr_b16 v[88:89], v158 offset:0x3000
	v_exp_f32_e32 v104, v95
	ds_read_b64_tr_b16 v[90:91], v158 offset:0x3800
	v_mfma_f32_32x32x16_bf16 v[16:31], v[132:135], v[146:149], v[16:31]
	s_waitcnt lgkmcnt(0)
	v_exp_f32_e32 v132, v68
	v_exp_f32_e32 v133, v69
	v_cvt_pk_bf16_f32 v68, v100, v101
	v_cvt_pk_bf16_f32 v69, v102, v103
	v_exp_f32_e32 v134, v74
	v_exp_f32_e32 v135, v75
	v_mfma_f32_32x32x16_bf16 v[0:15], v[64:67], v[70:73], v[0:15]
	v_cvt_pk_bf16_f32 v70, v124, v125
	v_cvt_pk_bf16_f32 v71, v126, v104
	v_cvt_pk_bf16_f32 v72, v105, v106
	v_cvt_pk_bf16_f32 v73, v107, v127
	v_cvt_pk_bf16_f32 v74, v132, v133
	v_cvt_pk_bf16_f32 v75, v108, v109
	v_cvt_pk_bf16_f32 v76, v110, v111
	v_mfma_f32_32x32x16_bf16 v[0:15], v[68:71], v[80:83], v[0:15]
	ds_read_b64_tr_b16 v[80:81], v158 offset:0x200
	ds_read_b64_tr_b16 v[82:83], v158 offset:0xa00
	v_mfma_f32_32x32x16_bf16 v[16:31], v[128:131], v[150:153], v[16:31]
	v_mfma_f32_32x32x16_bf16 v[0:15], v[72:75], v[84:87], v[0:15]
	ds_read_b64_tr_b16 v[84:85], v158 offset:0x1200
	ds_read_b64_tr_b16 v[86:87], v158 offset:0x1a00
	ds_read_b64_tr_b16 v[92:93], v158 offset:0x2200
	ds_read_b64_tr_b16 v[94:95], v158 offset:0x2a00
	ds_read_b64_tr_b16 v[96:97], v158 offset:0x3200
	ds_read_b64_tr_b16 v[98:99], v158 offset:0x3a00
	s_nop 0
	s_waitcnt lgkmcnt(0)
	v_mfma_f32_32x32x16_bf16 v[48:63], v[128:131], v[112:115], v[48:63]
	v_exp_f32_e32 v112, v77
	v_exp_f32_e32 v113, v78
	v_exp_f32_e32 v114, v79
	v_cvt_pk_bf16_f32 v77, v134, v135
	v_cvt_pk_bf16_f32 v78, v136, v112
	v_cvt_pk_bf16_f32 v79, v113, v114
	v_mfma_f32_32x32x16_bf16 v[16:31], v[64:67], v[80:83], v[16:31]
	v_add_f32_e32 v80, v144, v116
	v_add_f32_e32 v80, v117, v80
	v_add_f32_e32 v80, v118, v80
	v_add_f32_e32 v80, v119, v80
	v_add_f32_e32 v115, v120, v80
	ds_read_b64_tr_b16 v[80:81], v158 offset:0x400
	ds_read_b64_tr_b16 v[82:83], v158 offset:0xc00
	v_mfma_f32_32x32x16_bf16 v[16:31], v[68:71], v[84:87], v[16:31]
	ds_read_b64_tr_b16 v[84:85], v158 offset:0x1400
	ds_read_b64_tr_b16 v[86:87], v158 offset:0x1c00
	v_mfma_f32_32x32x16_bf16 v[0:15], v[76:79], v[88:91], v[0:15]
	ds_read_b64_tr_b16 v[88:89], v158 offset:0x2400
	ds_read_b64_tr_b16 v[90:91], v158 offset:0x2c00
	v_mfma_f32_32x32x16_bf16 v[16:31], v[72:75], v[92:95], v[16:31]
	ds_read_b64_tr_b16 v[92:93], v158 offset:0x3400
	ds_read_b64_tr_b16 v[94:95], v158 offset:0x3c00
	s_nop 0
	s_waitcnt lgkmcnt(0)
	s_nop 0
	v_mfma_f32_32x32x16_bf16 v[32:47], v[64:67], v[80:83], v[32:47]
	v_add_f32_e32 v80, v121, v115
	v_add_f32_e32 v80, v122, v80
	v_add_f32_e32 v80, v123, v80
	v_add_f32_e32 v80, v100, v80
	v_add_f32_e32 v80, v101, v80
	v_add_f32_e32 v80, v102, v80
	v_add_f32_e32 v80, v103, v80
	v_add_f32_e32 v80, v124, v80
	v_add_f32_e32 v80, v125, v80
	v_mfma_f32_32x32x16_bf16 v[32:47], v[68:71], v[84:87], v[32:47]
	v_add_f32_e32 v80, v126, v80
	v_add_f32_e32 v80, v104, v80
	v_add_f32_e32 v80, v105, v80
	v_add_f32_e32 v80, v106, v80
	v_add_f32_e32 v100, v107, v80
	ds_read_b64_tr_b16 v[80:81], v158 offset:0x600
	ds_read_b64_tr_b16 v[82:83], v158 offset:0xe00
	ds_read_b64_tr_b16 v[84:85], v158 offset:0x1600
	ds_read_b64_tr_b16 v[86:87], v158 offset:0x1e00
	v_mfma_f32_32x32x16_bf16 v[32:47], v[72:75], v[88:91], v[32:47]
	ds_read_b64_tr_b16 v[88:89], v158 offset:0x2600
	ds_read_b64_tr_b16 v[90:91], v158 offset:0x2e00
	v_mfma_f32_32x32x16_bf16 v[16:31], v[76:79], v[96:99], v[16:31]
	ds_read_b64_tr_b16 v[96:97], v158 offset:0x3600
	ds_read_b64_tr_b16 v[98:99], v158 offset:0x3e00
	s_nop 0
	s_waitcnt lgkmcnt(0)
	s_waitcnt vmcnt(0) lgkmcnt(0)
	s_barrier
	v_mfma_f32_32x32x16_bf16 v[48:63], v[64:67], v[80:83], v[48:63]
	v_add_f32_e32 v64, v127, v100
	v_add_f32_e32 v64, v132, v64
	v_add_f32_e32 v64, v133, v64
	v_add_f32_e32 v64, v108, v64
	v_add_f32_e32 v64, v109, v64
	v_add_f32_e32 v64, v110, v64
	v_add_f32_e32 v64, v111, v64
	v_mfma_f32_32x32x16_bf16 v[48:63], v[68:71], v[84:87], v[48:63]
	v_add_f32_e32 v64, v134, v64
	v_add_f32_e32 v64, v135, v64
	v_add_f32_e32 v64, v136, v64
	v_add_f32_e32 v64, v112, v64
	v_add_f32_e32 v64, v113, v64
	v_add_f32_e32 v66, v114, v64
	v_mov_b32_e32 v67, v66
	v_mfma_f32_32x32x16_bf16 v[48:63], v[72:75], v[88:91], v[48:63]
	s_nop 0
	v_permlane32_swap_b32_e32 v66, v67
	v_mbcnt_lo_u32_b32 v64, -1, 0
	v_mbcnt_hi_u32_b32 v64, -1, v64
	s_nop 0
	v_and_b32_e32 v65, 31, v64
	v_cmp_gt_u32_e32 vcc, 32, v64
	v_mfma_f32_32x32x16_bf16 v[32:47], v[76:79], v[92:95], v[32:47]
	v_mfma_f32_32x32x16_bf16 v[48:63], v[76:79], v[96:99], v[48:63]
	s_and_saveexec_b64 s[12:13], vcc
	s_cbranch_execz .LBB0_37
	v_lshl_add_u32 v68, v65, 2, s20
	v_add_f32_e32 v66, v66, v67
	ds_write_b32 v68, v66
	s_branch .LBB0_37

;     __device__ __forceinline__ void operator()(const f32x4 (&acc)[2][2][4][2], const Unit& u, int wr, int wc, int fr, int fq) const {
;         const int rowt = u.pm * BM;
;         const float* base = (rowt < MP ? baseP + (size_t)rowt * DM : baseS + (size_t)(rowt - MP) * DM) + u.pn * BM;
;         float* o = out + (size_t)rowt * DM + u.pn * BM;
;         unsigned lo = (unsigned)((wr * 64 + fr) * DM + wc * 32 + 4 * fq); asm volatile("" : "+v"(lo));
; #pragma unroll
;         for (int ai = 0; ai < 2; ++ai)
; #pragma unroll
;             for (int m = 0; m < 4; ++m) { const unsigned off = lo + (unsigned)((ai * HALF + m * 16) * DM);
; #pragma unroll
;                 for (int bj = 0; bj < 2; ++bj) {
;                     const f32x4 b0 = *(const f32x4*)(base + off + bj * HALF), b1 = *(const f32x4*)(base + off + bj * HALF + 16);
;                     *(f32x4*)(o + off + bj * HALF) = b0 + acc[ai][bj][m][0] * scale; *(f32x4*)(o + off + bj * HALF + 16) = b1 + acc[ai][bj][m][1] * scale; }
;                 asm volatile("" ::: "memory"); }
;     }
.LBB0_174:
	s_lshl_b32 s22, s42, 8
	s_ashr_i32 s23, s22, 31
	s_lshl_b64 s[22:23], s[22:23], 2
	s_add_u32 s18, s18, s22
	s_addc_u32 s19, s19, s23
	v_readlane_b32 s44, v253, 7
	v_readlane_b32 s46, v253, 9
	v_readlane_b32 s47, v253, 10
	s_add_u32 s5, s46, s20
	s_addc_u32 s13, s47, s21
	s_add_u32 s20, s5, s22
	s_addc_u32 s21, s13, s23
	s_andn2_b64 vcc, exec, s[10:11]
	s_mov_b64 s[10:11], -1
	v_readlane_b32 s45, v253, 8
	v_add_u32_e32 v160, 0x0, v137
	v_lshl_add_u64 v[140:141], v[160:161], 2, s[18:19]
	v_lshl_add_u64 v[142:143], v[160:161], 2, s[20:21]
	global_load_dwordx4 v[166:169], v[140:141], off
	global_load_dwordx4 v[170:173], v[140:141], off offset:64
	global_load_dwordx4 v[174:177], v[140:141], off offset:512
	global_load_dwordx4 v[178:181], v[140:141], off offset:576
	v_add_u32_e32 v160, 0x8000, v137
	v_lshl_add_u64 v[144:145], v[160:161], 2, s[18:19]
	v_lshl_add_u64 v[146:147], v[160:161], 2, s[20:21]
	global_load_dwordx4 v[182:185], v[144:145], off
	global_load_dwordx4 v[186:189], v[144:145], off offset:64
	global_load_dwordx4 v[190:193], v[144:145], off offset:512
	global_load_dwordx4 v[194:197], v[144:145], off offset:576
	v_add_u32_e32 v160, 0x10000, v137
	v_lshl_add_u64 v[148:149], v[160:161], 2, s[18:19]
	v_lshl_add_u64 v[150:151], v[160:161], 2, s[20:21]
	global_load_dwordx4 v[198:201], v[148:149], off
	global_load_dwordx4 v[212:215], v[148:149], off offset:64
	global_load_dwordx4 v[216:219], v[148:149], off offset:512
	global_load_dwordx4 v[156:159], v[148:149], off offset:576
	s_waitcnt vmcnt(8)
	v_pk_add_f32 v[166:167], v[124:125], v[166:167]
	v_pk_add_f32 v[168:169], v[126:127], v[168:169]
	v_pk_add_f32 v[170:171], v[120:121], v[170:171]
	v_pk_add_f32 v[172:173], v[122:123], v[172:173]
	v_pk_add_f32 v[174:175], v[112:113], v[174:175]
	v_pk_add_f32 v[176:177], v[114:115], v[176:177]
	v_pk_add_f32 v[178:179], v[104:105], v[178:179]
	v_pk_add_f32 v[180:181], v[106:107], v[180:181]
	global_store_dwordx4 v[142:143], v[166:169], off
	global_store_dwordx4 v[142:143], v[170:173], off offset:64
	global_store_dwordx4 v[142:143], v[174:177], off offset:512
	global_store_dwordx4 v[142:143], v[178:181], off offset:576
	v_add_u32_e32 v160, 0x18000, v137
	v_lshl_add_u64 v[152:153], v[160:161], 2, s[18:19]
	v_lshl_add_u64 v[154:155], v[160:161], 2, s[20:21]
	global_load_dwordx4 v[166:169], v[152:153], off
	global_load_dwordx4 v[170:173], v[152:153], off offset:64
	global_load_dwordx4 v[174:177], v[152:153], off offset:512
	global_load_dwordx4 v[178:181], v[152:153], off offset:576
	s_waitcnt vmcnt(12)
	v_pk_add_f32 v[182:183], v[116:117], v[182:183]
	v_pk_add_f32 v[184:185], v[118:119], v[184:185]
	v_pk_add_f32 v[186:187], v[108:109], v[186:187]
	v_pk_add_f32 v[188:189], v[110:111], v[188:189]
	v_pk_add_f32 v[190:191], v[96:97], v[190:191]
	v_pk_add_f32 v[192:193], v[98:99], v[192:193]
	v_pk_add_f32 v[194:195], v[88:89], v[194:195]
	v_pk_add_f32 v[196:197], v[90:91], v[196:197]
	global_store_dwordx4 v[146:147], v[182:185], off
	global_store_dwordx4 v[146:147], v[186:189], off offset:64
	global_store_dwordx4 v[146:147], v[190:193], off offset:512
	global_store_dwordx4 v[146:147], v[194:197], off offset:576
	v_add_u32_e32 v160, 0x40000, v137
	v_lshl_add_u64 v[140:141], v[160:161], 2, s[18:19]
	v_lshl_add_u64 v[142:143], v[160:161], 2, s[20:21]
	global_load_dwordx4 v[182:185], v[140:141], off
	global_load_dwordx4 v[186:189], v[140:141], off offset:64
	global_load_dwordx4 v[190:193], v[140:141], off offset:512
	global_load_dwordx4 v[194:197], v[140:141], off offset:576
	s_waitcnt vmcnt(16)
	v_pk_add_f32 v[198:199], v[100:101], v[198:199]
	v_pk_add_f32 v[200:201], v[102:103], v[200:201]
	v_pk_add_f32 v[212:213], v[92:93], v[212:213]
	v_pk_add_f32 v[214:215], v[94:95], v[214:215]
	v_pk_add_f32 v[216:217], v[80:81], v[216:217]
	v_pk_add_f32 v[218:219], v[82:83], v[218:219]
	v_pk_add_f32 v[156:157], v[72:73], v[156:157]
	v_pk_add_f32 v[158:159], v[74:75], v[158:159]
	global_store_dwordx4 v[150:151], v[198:201], off
	global_store_dwordx4 v[150:151], v[212:215], off offset:64
	global_store_dwordx4 v[150:151], v[216:219], off offset:512
	global_store_dwordx4 v[150:151], v[156:159], off offset:576
	v_add_u32_e32 v160, 0x48000, v137
	v_lshl_add_u64 v[144:145], v[160:161], 2, s[18:19]
	v_lshl_add_u64 v[146:147], v[160:161], 2, s[20:21]
	global_load_dwordx4 v[198:201], v[144:145], off
	global_load_dwordx4 v[212:215], v[144:145], off offset:64
	global_load_dwordx4 v[216:219], v[144:145], off offset:512
	global_load_dwordx4 v[156:159], v[144:145], off offset:576
	s_waitcnt vmcnt(16)
;     __device__ __forceinline__ void operator()(const f32x4 (&acc)[2][2][4][2], const Unit& u, int wr, int wc, int fr, int fq) const {
;         const int rowt = u.pm * BM;
;         const float* base = (rowt < MP ? baseP + (size_t)rowt * DM : baseS + (size_t)(rowt - MP) * DM) + u.pn * BM;
;         float* o = out + (size_t)rowt * DM + u.pn * BM;
;         unsigned lo = (unsigned)((wr * 64 + fr) * DM + wc * 32 + 4 * fq); asm volatile("" : "+v"(lo));
; #pragma unroll
;         for (int ai = 0; ai < 2; ++ai)
; #pragma unroll
;             for (int m = 0; m < 4; ++m) { const unsigned off = lo + (unsigned)((ai * HALF + m * 16) * DM);
; #pragma unroll
;                 for (int bj = 0; bj < 2; ++bj) {
;                     const f32x4 b0 = *(const f32x4*)(base + off + bj * HALF), b1 = *(const f32x4*)(base + off + bj * HALF + 16);
;                     *(f32x4*)(o + off + bj * HALF) = b0 + acc[ai][bj][m][0] * scale; *(f32x4*)(o + off + bj * HALF + 16) = b1 + acc[ai][bj][m][1] * scale; }
;                 asm volatile("" ::: "memory"); }
;     }
	v_pk_add_f32 v[166:167], v[84:85], v[166:167]
	v_pk_add_f32 v[168:169], v[86:87], v[168:169]
	v_pk_add_f32 v[170:171], v[76:77], v[170:171]
	v_pk_add_f32 v[172:173], v[78:79], v[172:173]
	v_pk_add_f32 v[174:175], v[68:69], v[174:175]
	v_pk_add_f32 v[176:177], v[70:71], v[176:177]
	v_pk_add_f32 v[178:179], v[64:65], v[178:179]
	v_pk_add_f32 v[180:181], v[66:67], v[180:181]
	global_store_dwordx4 v[154:155], v[166:169], off
	global_store_dwordx4 v[154:155], v[170:173], off offset:64
	global_store_dwordx4 v[154:155], v[174:177], off offset:512
	global_store_dwordx4 v[154:155], v[178:181], off offset:576
	v_add_u32_e32 v160, 0x50000, v137
	v_lshl_add_u64 v[148:149], v[160:161], 2, s[18:19]
	v_lshl_add_u64 v[150:151], v[160:161], 2, s[20:21]
	global_load_dwordx4 v[166:169], v[148:149], off
	global_load_dwordx4 v[170:173], v[148:149], off offset:64
	global_load_dwordx4 v[174:177], v[148:149], off offset:512
	global_load_dwordx4 v[178:181], v[148:149], off offset:576
	s_waitcnt vmcnt(16)
	v_pk_add_f32 v[182:183], v[60:61], v[182:183]
	v_pk_add_f32 v[184:185], v[62:63], v[184:185]
	v_pk_add_f32 v[186:187], v[56:57], v[186:187]
	v_pk_add_f32 v[188:189], v[58:59], v[188:189]
	v_pk_add_f32 v[190:191], v[48:49], v[190:191]
	v_pk_add_f32 v[192:193], v[50:51], v[192:193]
	v_pk_add_f32 v[194:195], v[40:41], v[194:195]
	v_pk_add_f32 v[196:197], v[42:43], v[196:197]
	global_store_dwordx4 v[142:143], v[182:185], off
	global_store_dwordx4 v[142:143], v[186:189], off offset:64
	global_store_dwordx4 v[142:143], v[190:193], off offset:512
	global_store_dwordx4 v[142:143], v[194:197], off offset:576
	v_add_u32_e32 v160, 0x58000, v137
	v_lshl_add_u64 v[152:153], v[160:161], 2, s[18:19]
	v_lshl_add_u64 v[154:155], v[160:161], 2, s[20:21]
	global_load_dwordx4 v[182:185], v[152:153], off
	global_load_dwordx4 v[186:189], v[152:153], off offset:64
	global_load_dwordx4 v[190:193], v[152:153], off offset:512
	global_load_dwordx4 v[194:197], v[152:153], off offset:576
	s_waitcnt vmcnt(16)
	v_pk_add_f32 v[198:199], v[52:53], v[198:199]
	v_pk_add_f32 v[200:201], v[54:55], v[200:201]
	v_pk_add_f32 v[212:213], v[44:45], v[212:213]
	v_pk_add_f32 v[214:215], v[46:47], v[214:215]
	v_pk_add_f32 v[216:217], v[32:33], v[216:217]
	v_pk_add_f32 v[218:219], v[34:35], v[218:219]
	v_pk_add_f32 v[156:157], v[24:25], v[156:157]
	v_pk_add_f32 v[158:159], v[26:27], v[158:159]
	global_store_dwordx4 v[146:147], v[198:201], off
	global_store_dwordx4 v[146:147], v[212:215], off offset:64
	global_store_dwordx4 v[146:147], v[216:219], off offset:512
	global_store_dwordx4 v[146:147], v[156:159], off offset:576
	s_waitcnt vmcnt(12)
	v_pk_add_f32 v[166:167], v[36:37], v[166:167]
	v_pk_add_f32 v[168:169], v[38:39], v[168:169]
	v_pk_add_f32 v[170:171], v[28:29], v[170:171]
	v_pk_add_f32 v[172:173], v[30:31], v[172:173]
	v_pk_add_f32 v[174:175], v[16:17], v[174:175]
	v_pk_add_f32 v[176:177], v[18:19], v[176:177]
	v_pk_add_f32 v[178:179], v[8:9], v[178:179]
	v_pk_add_f32 v[180:181], v[10:11], v[180:181]
	global_store_dwordx4 v[150:151], v[166:169], off
	global_store_dwordx4 v[150:151], v[170:173], off offset:64
	global_store_dwordx4 v[150:151], v[174:177], off offset:512
	global_store_dwordx4 v[150:151], v[178:181], off offset:576
	s_waitcnt vmcnt(8)
	v_pk_add_f32 v[182:183], v[20:21], v[182:183]
	v_pk_add_f32 v[184:185], v[22:23], v[184:185]
	v_pk_add_f32 v[186:187], v[12:13], v[186:187]
	v_pk_add_f32 v[188:189], v[14:15], v[188:189]
	v_pk_add_f32 v[190:191], v[4:5], v[190:191]
	v_pk_add_f32 v[192:193], v[6:7], v[192:193]
	v_pk_add_f32 v[194:195], v[0:1], v[194:195]
	v_pk_add_f32 v[196:197], v[2:3], v[196:197]
	global_store_dwordx4 v[154:155], v[182:185], off
	global_store_dwordx4 v[154:155], v[186:189], off offset:64
	global_store_dwordx4 v[154:155], v[190:193], off offset:512
	global_store_dwordx4 v[154:155], v[194:197], off offset:576
	v_add_u32_e32 v160, 0x58000, v137
	s_cbranch_vccnz .LBB0_163
	s_andn2_b64 vcc, exec, s[0:1]
	s_cbranch_vccnz .LBB0_162
	s_barrier
	s_branch .LBB0_162

;     __device__ __forceinline__ void operator()(const f32x4 (&acc)[2][2][4][2], const Unit& u, int wr, int wc, int fr, int fq) const {
;         const int rowt = u.pm * BM;
;         const float* base = (rowt < MP ? baseP + (size_t)rowt * DM : baseS + (size_t)(rowt - MP) * DM) + u.pn * BM;
;         float* o = out + (size_t)rowt * DM + u.pn * BM;
;         unsigned lo = (unsigned)((wr * 64 + fr) * DM + wc * 32 + 4 * fq); asm volatile("" : "+v"(lo));
; #pragma unroll
;         for (int ai = 0; ai < 2; ++ai)
; #pragma unroll
;             for (int m = 0; m < 4; ++m) { const unsigned off = lo + (unsigned)((ai * HALF + m * 16) * DM);
; #pragma unroll
;                 for (int bj = 0; bj < 2; ++bj) {
;                     const f32x4 b0 = *(const f32x4*)(base + off + bj * HALF), b1 = *(const f32x4*)(base + off + bj * HALF + 16);
;                     *(f32x4*)(o + off + bj * HALF) = b0 + acc[ai][bj][m][0] * scale; *(f32x4*)(o + off + bj * HALF + 16) = b1 + acc[ai][bj][m][1] * scale; }
;                 asm volatile("" ::: "memory"); }
;     }
.LBB0_196:
	s_lshl_b32 s22, s41, 8
	s_ashr_i32 s23, s22, 31
	s_lshl_b64 s[22:23], s[22:23], 2
	s_add_u32 s18, s18, s22
	s_addc_u32 s19, s19, s23
	v_readlane_b32 s44, v253, 7
	v_readlane_b32 s46, v253, 9
	v_readlane_b32 s47, v253, 10
	s_add_u32 s5, s46, s20
	s_addc_u32 s13, s47, s21
	s_add_u32 s20, s5, s22
	s_addc_u32 s21, s13, s23
	s_andn2_b64 vcc, exec, s[10:11]
	s_mov_b64 s[10:11], -1
	v_readlane_b32 s45, v253, 8
	v_add_u32_e32 v160, 0x0, v184
	v_lshl_add_u64 v[216:217], v[160:161], 2, s[18:19]
	v_lshl_add_u64 v[218:219], v[160:161], 2, s[20:21]
	global_load_dwordx4 v[12:15], v[216:217], off
	global_load_dwordx4 v[16:19], v[216:217], off offset:64
	global_load_dwordx4 v[20:23], v[216:217], off offset:512
	global_load_dwordx4 v[24:27], v[216:217], off offset:576
	v_add_u32_e32 v160, 0x8000, v184
	v_lshl_add_u64 v[220:221], v[160:161], 2, s[18:19]
	v_lshl_add_u64 v[222:223], v[160:161], 2, s[20:21]
	global_load_dwordx4 v[28:31], v[220:221], off
	global_load_dwordx4 v[174:177], v[220:221], off offset:64
	global_load_dwordx4 v[178:181], v[220:221], off offset:512
	global_load_dwordx4 v[186:189], v[220:221], off offset:576
	v_add_u32_e32 v160, 0x10000, v184
	v_lshl_add_u64 v[224:225], v[160:161], 2, s[18:19]
	v_lshl_add_u64 v[226:227], v[160:161], 2, s[20:21]
	global_load_dwordx4 v[190:193], v[224:225], off
	global_load_dwordx4 v[194:197], v[224:225], off offset:64
	global_load_dwordx4 v[198:201], v[224:225], off offset:512
	global_load_dwordx4 v[212:215], v[224:225], off offset:576
	s_waitcnt vmcnt(8)
	v_pk_fma_f32 v[12:13], v[156:157], s[96:97], v[12:13] op_sel_hi:[1,0,1]
	v_pk_fma_f32 v[14:15], v[158:159], s[96:97], v[14:15] op_sel_hi:[1,0,1]
	v_pk_fma_f32 v[16:17], v[152:153], s[96:97], v[16:17] op_sel_hi:[1,0,1]
	v_pk_fma_f32 v[18:19], v[154:155], s[96:97], v[18:19] op_sel_hi:[1,0,1]
	v_pk_fma_f32 v[20:21], v[144:145], s[96:97], v[20:21] op_sel_hi:[1,0,1]
	v_pk_fma_f32 v[22:23], v[146:147], s[96:97], v[22:23] op_sel_hi:[1,0,1]
	v_pk_fma_f32 v[24:25], v[136:137], s[96:97], v[24:25] op_sel_hi:[1,0,1]
	v_pk_fma_f32 v[26:27], v[138:139], s[96:97], v[26:27] op_sel_hi:[1,0,1]
	global_store_dwordx4 v[218:219], v[12:15], off
	global_store_dwordx4 v[218:219], v[16:19], off offset:64
	global_store_dwordx4 v[218:219], v[20:23], off offset:512
	global_store_dwordx4 v[218:219], v[24:27], off offset:576
	v_add_u32_e32 v160, 0x18000, v184
	v_lshl_add_u64 v[0:1], v[160:161], 2, s[18:19]
	v_lshl_add_u64 v[2:3], v[160:161], 2, s[20:21]
	global_load_dwordx4 v[12:15], v[0:1], off
	global_load_dwordx4 v[16:19], v[0:1], off offset:64
	global_load_dwordx4 v[20:23], v[0:1], off offset:512
	global_load_dwordx4 v[24:27], v[0:1], off offset:576
	s_waitcnt vmcnt(12)
	v_pk_fma_f32 v[28:29], v[148:149], s[96:97], v[28:29] op_sel_hi:[1,0,1]
	v_pk_fma_f32 v[30:31], v[150:151], s[96:97], v[30:31] op_sel_hi:[1,0,1]
	v_pk_fma_f32 v[174:175], v[140:141], s[96:97], v[174:175] op_sel_hi:[1,0,1]
	v_pk_fma_f32 v[176:177], v[142:143], s[96:97], v[176:177] op_sel_hi:[1,0,1]
	v_pk_fma_f32 v[178:179], v[128:129], s[96:97], v[178:179] op_sel_hi:[1,0,1]
	v_pk_fma_f32 v[180:181], v[130:131], s[96:97], v[180:181] op_sel_hi:[1,0,1]
	v_pk_fma_f32 v[186:187], v[120:121], s[96:97], v[186:187] op_sel_hi:[1,0,1]
	v_pk_fma_f32 v[188:189], v[122:123], s[96:97], v[188:189] op_sel_hi:[1,0,1]
	global_store_dwordx4 v[222:223], v[28:31], off
	global_store_dwordx4 v[222:223], v[174:177], off offset:64
	global_store_dwordx4 v[222:223], v[178:181], off offset:512
	global_store_dwordx4 v[222:223], v[186:189], off offset:576
	v_add_u32_e32 v160, 0x40000, v184
	v_lshl_add_u64 v[216:217], v[160:161], 2, s[18:19]
	v_lshl_add_u64 v[218:219], v[160:161], 2, s[20:21]
	global_load_dwordx4 v[28:31], v[216:217], off
	global_load_dwordx4 v[174:177], v[216:217], off offset:64
	global_load_dwordx4 v[178:181], v[216:217], off offset:512
	global_load_dwordx4 v[186:189], v[216:217], off offset:576
	s_waitcnt vmcnt(16)
	v_pk_fma_f32 v[190:191], v[132:133], s[96:97], v[190:191] op_sel_hi:[1,0,1]
	v_pk_fma_f32 v[192:193], v[134:135], s[96:97], v[192:193] op_sel_hi:[1,0,1]
	v_pk_fma_f32 v[194:195], v[124:125], s[96:97], v[194:195] op_sel_hi:[1,0,1]
	v_pk_fma_f32 v[196:197], v[126:127], s[96:97], v[196:197] op_sel_hi:[1,0,1]
	v_pk_fma_f32 v[198:199], v[112:113], s[96:97], v[198:199] op_sel_hi:[1,0,1]
	v_pk_fma_f32 v[200:201], v[114:115], s[96:97], v[200:201] op_sel_hi:[1,0,1]
	v_pk_fma_f32 v[212:213], v[104:105], s[96:97], v[212:213] op_sel_hi:[1,0,1]
	v_pk_fma_f32 v[214:215], v[106:107], s[96:97], v[214:215] op_sel_hi:[1,0,1]
	global_store_dwordx4 v[226:227], v[190:193], off
	global_store_dwordx4 v[226:227], v[194:197], off offset:64
	global_store_dwordx4 v[226:227], v[198:201], off offset:512
	global_store_dwordx4 v[226:227], v[212:215], off offset:576
	v_add_u32_e32 v160, 0x48000, v184
	v_lshl_add_u64 v[220:221], v[160:161], 2, s[18:19]
	v_lshl_add_u64 v[222:223], v[160:161], 2, s[20:21]
	global_load_dwordx4 v[190:193], v[220:221], off
	global_load_dwordx4 v[194:197], v[220:221], off offset:64
	global_load_dwordx4 v[198:201], v[220:221], off offset:512
	global_load_dwordx4 v[212:215], v[220:221], off offset:576
	s_waitcnt vmcnt(16)
;     __device__ __forceinline__ void operator()(const f32x4 (&acc)[2][2][4][2], const Unit& u, int wr, int wc, int fr, int fq) const {
;         const int rowt = u.pm * BM;
;         const float* base = (rowt < MP ? baseP + (size_t)rowt * DM : baseS + (size_t)(rowt - MP) * DM) + u.pn * BM;
;         float* o = out + (size_t)rowt * DM + u.pn * BM;
;         unsigned lo = (unsigned)((wr * 64 + fr) * DM + wc * 32 + 4 * fq); asm volatile("" : "+v"(lo));
; #pragma unroll
;         for (int ai = 0; ai < 2; ++ai)
; #pragma unroll
;             for (int m = 0; m < 4; ++m) { const unsigned off = lo + (unsigned)((ai * HALF + m * 16) * DM);
; #pragma unroll
;                 for (int bj = 0; bj < 2; ++bj) {
;                     const f32x4 b0 = *(const f32x4*)(base + off + bj * HALF), b1 = *(const f32x4*)(base + off + bj * HALF + 16);
;                     *(f32x4*)(o + off + bj * HALF) = b0 + acc[ai][bj][m][0] * scale; *(f32x4*)(o + off + bj * HALF + 16) = b1 + acc[ai][bj][m][1] * scale; }
;                 asm volatile("" ::: "memory"); }
;     }
	v_pk_fma_f32 v[12:13], v[116:117], s[96:97], v[12:13] op_sel_hi:[1,0,1]
	v_pk_fma_f32 v[14:15], v[118:119], s[96:97], v[14:15] op_sel_hi:[1,0,1]
	v_pk_fma_f32 v[16:17], v[108:109], s[96:97], v[16:17] op_sel_hi:[1,0,1]
	v_pk_fma_f32 v[18:19], v[110:111], s[96:97], v[18:19] op_sel_hi:[1,0,1]
	v_pk_fma_f32 v[20:21], v[100:101], s[96:97], v[20:21] op_sel_hi:[1,0,1]
	v_pk_fma_f32 v[22:23], v[102:103], s[96:97], v[22:23] op_sel_hi:[1,0,1]
	v_pk_fma_f32 v[24:25], v[96:97], s[96:97], v[24:25] op_sel_hi:[1,0,1]
	v_pk_fma_f32 v[26:27], v[98:99], s[96:97], v[26:27] op_sel_hi:[1,0,1]
	global_store_dwordx4 v[2:3], v[12:15], off
	global_store_dwordx4 v[2:3], v[16:19], off offset:64
	global_store_dwordx4 v[2:3], v[20:23], off offset:512
	global_store_dwordx4 v[2:3], v[24:27], off offset:576
	v_add_u32_e32 v160, 0x50000, v184
	v_lshl_add_u64 v[224:225], v[160:161], 2, s[18:19]
	v_lshl_add_u64 v[226:227], v[160:161], 2, s[20:21]
	global_load_dwordx4 v[12:15], v[224:225], off
	global_load_dwordx4 v[16:19], v[224:225], off offset:64
	global_load_dwordx4 v[20:23], v[224:225], off offset:512
	global_load_dwordx4 v[24:27], v[224:225], off offset:576
	s_waitcnt vmcnt(16)
	v_pk_fma_f32 v[28:29], v[92:93], s[96:97], v[28:29] op_sel_hi:[1,0,1]
	v_pk_fma_f32 v[30:31], v[94:95], s[96:97], v[30:31] op_sel_hi:[1,0,1]
	v_pk_fma_f32 v[174:175], v[88:89], s[96:97], v[174:175] op_sel_hi:[1,0,1]
	v_pk_fma_f32 v[176:177], v[90:91], s[96:97], v[176:177] op_sel_hi:[1,0,1]
	v_pk_fma_f32 v[178:179], v[80:81], s[96:97], v[178:179] op_sel_hi:[1,0,1]
	v_pk_fma_f32 v[180:181], v[82:83], s[96:97], v[180:181] op_sel_hi:[1,0,1]
	v_pk_fma_f32 v[186:187], v[72:73], s[96:97], v[186:187] op_sel_hi:[1,0,1]
	v_pk_fma_f32 v[188:189], v[74:75], s[96:97], v[188:189] op_sel_hi:[1,0,1]
	global_store_dwordx4 v[218:219], v[28:31], off
	global_store_dwordx4 v[218:219], v[174:177], off offset:64
	global_store_dwordx4 v[218:219], v[178:181], off offset:512
	global_store_dwordx4 v[218:219], v[186:189], off offset:576
	v_add_u32_e32 v160, 0x58000, v184
	v_lshl_add_u64 v[0:1], v[160:161], 2, s[18:19]
	v_lshl_add_u64 v[2:3], v[160:161], 2, s[20:21]
	global_load_dwordx4 v[28:31], v[0:1], off
	global_load_dwordx4 v[174:177], v[0:1], off offset:64
	global_load_dwordx4 v[178:181], v[0:1], off offset:512
	global_load_dwordx4 v[186:189], v[0:1], off offset:576
	s_waitcnt vmcnt(16)
	v_pk_fma_f32 v[190:191], v[84:85], s[96:97], v[190:191] op_sel_hi:[1,0,1]
	v_pk_fma_f32 v[192:193], v[86:87], s[96:97], v[192:193] op_sel_hi:[1,0,1]
	v_pk_fma_f32 v[194:195], v[76:77], s[96:97], v[194:195] op_sel_hi:[1,0,1]
	v_pk_fma_f32 v[196:197], v[78:79], s[96:97], v[196:197] op_sel_hi:[1,0,1]
	v_pk_fma_f32 v[198:199], v[64:65], s[96:97], v[198:199] op_sel_hi:[1,0,1]
	v_pk_fma_f32 v[200:201], v[66:67], s[96:97], v[200:201] op_sel_hi:[1,0,1]
	v_pk_fma_f32 v[212:213], v[56:57], s[96:97], v[212:213] op_sel_hi:[1,0,1]
	v_pk_fma_f32 v[214:215], v[58:59], s[96:97], v[214:215] op_sel_hi:[1,0,1]
	global_store_dwordx4 v[222:223], v[190:193], off
	global_store_dwordx4 v[222:223], v[194:197], off offset:64
	global_store_dwordx4 v[222:223], v[198:201], off offset:512
	global_store_dwordx4 v[222:223], v[212:215], off offset:576
	s_waitcnt vmcnt(12)
	v_pk_fma_f32 v[12:13], v[68:69], s[96:97], v[12:13] op_sel_hi:[1,0,1]
	v_pk_fma_f32 v[14:15], v[70:71], s[96:97], v[14:15] op_sel_hi:[1,0,1]
	v_pk_fma_f32 v[16:17], v[60:61], s[96:97], v[16:17] op_sel_hi:[1,0,1]
	v_pk_fma_f32 v[18:19], v[62:63], s[96:97], v[18:19] op_sel_hi:[1,0,1]
	v_pk_fma_f32 v[20:21], v[48:49], s[96:97], v[20:21] op_sel_hi:[1,0,1]
	v_pk_fma_f32 v[22:23], v[50:51], s[96:97], v[22:23] op_sel_hi:[1,0,1]
	v_pk_fma_f32 v[24:25], v[40:41], s[96:97], v[24:25] op_sel_hi:[1,0,1]
	v_pk_fma_f32 v[26:27], v[42:43], s[96:97], v[26:27] op_sel_hi:[1,0,1]
	global_store_dwordx4 v[226:227], v[12:15], off
	global_store_dwordx4 v[226:227], v[16:19], off offset:64
	global_store_dwordx4 v[226:227], v[20:23], off offset:512
	global_store_dwordx4 v[226:227], v[24:27], off offset:576
	s_waitcnt vmcnt(8)
	v_pk_fma_f32 v[28:29], v[52:53], s[96:97], v[28:29] op_sel_hi:[1,0,1]
	v_pk_fma_f32 v[30:31], v[54:55], s[96:97], v[30:31] op_sel_hi:[1,0,1]
	v_pk_fma_f32 v[174:175], v[44:45], s[96:97], v[174:175] op_sel_hi:[1,0,1]
	v_pk_fma_f32 v[176:177], v[46:47], s[96:97], v[176:177] op_sel_hi:[1,0,1]
	v_pk_fma_f32 v[178:179], v[36:37], s[96:97], v[178:179] op_sel_hi:[1,0,1]
	v_pk_fma_f32 v[180:181], v[38:39], s[96:97], v[180:181] op_sel_hi:[1,0,1]
	v_pk_fma_f32 v[186:187], v[32:33], s[96:97], v[186:187] op_sel_hi:[1,0,1]
	v_pk_fma_f32 v[188:189], v[34:35], s[96:97], v[188:189] op_sel_hi:[1,0,1]
	global_store_dwordx4 v[2:3], v[28:31], off
	global_store_dwordx4 v[2:3], v[174:177], off offset:64
	global_store_dwordx4 v[2:3], v[178:181], off offset:512
	global_store_dwordx4 v[2:3], v[186:189], off offset:576
	v_add_u32_e32 v160, 0x58000, v184
	s_cbranch_vccnz .LBB0_185
	s_andn2_b64 vcc, exec, s[0:1]
	s_cbranch_vccnz .LBB0_184
	s_barrier
	s_branch .LBB0_184
